# adds hand-written merge_rows (16-byte accesses, two rows per wave instruction, 4 row pairs in flight) to the MFMA-kraw / wide-prep candidate
# speedup vs baseline: 1.0282x; 1.0062x over previous
; __device__ __forceinline__ float bf_lo(unsigned w) { return __uint_as_float(w << 16); }
; __device__ __forceinline__ float bf_hi(unsigned w) { return __uint_as_float(w & 0xffff0000u); }
; __device__ __forceinline__ unsigned pk2(float lo, float hi) { return pg8::cvt_pk_bf16(lo, hi); }
; __device__ __forceinline__ void merge_rows(const Args& a, int gw, int NGW, int lane) {
;     const bf16* OG = (const bf16*)(a.ws + WS_OG); const float* LSE = (const float*)(a.ws + WS_LSE); bf16* YAT = (bf16*)(a.ws + WS_YAT);
;     const int hh = lane >> 4;
;     for (int mb = gw; mb < MT; mb += 4 * NGW) {
;         float l[4][3]; v2u o[4][3];
; #pragma unroll
;         for (int r = 0; r < 4; ++r) { const int m = mb + r * NGW; const int mc = m < MT ? m : mb;
; #pragma unroll
;             for (int g = 0; g < 3; ++g) { l[r][g] = LSE[((size_t)g * MT + mc) * 4 + hh]; o[r][g] = *(const v2u*)(OG + ((size_t)g * MT + mc) * 256 + 4 * lane); } }
; #pragma unroll
;         for (int r = 0; r < 4; ++r) { const int m = mb + r * NGW; if (m < MT) {
;             const float mxl = fmaxf(l[r][0], fmaxf(l[r][1], l[r][2]));
;             float a0 = __expf(l[r][0] - mxl), a1 = __expf(l[r][1] - mxl), a2 = __expf(l[r][2] - mxl); const float is = 1.0f / (a0 + a1 + a2); a0 *= is; a1 *= is; a2 *= is;
;             const v2u o0 = o[r][0], o1 = o[r][1], o2 = o[r][2];
;             v2u w;
;             w.x = pk2(a0 * pg8::bf_lo(o0.x) + a1 * pg8::bf_lo(o1.x) + a2 * pg8::bf_lo(o2.x), a0 * pg8::bf_hi(o0.x) + a1 * pg8::bf_hi(o1.x) + a2 * pg8::bf_hi(o2.x));
;             w.y = pk2(a0 * pg8::bf_lo(o0.y) + a1 * pg8::bf_lo(o1.y) + a2 * pg8::bf_lo(o2.y), a0 * pg8::bf_hi(o0.y) + a1 * pg8::bf_hi(o1.y) + a2 * pg8::bf_hi(o2.y));
;             *(v2u*)(YAT + (size_t)m * 256 + 4 * lane) = w; } }
.LBB0_457:
	s_cmp_lt_i32 s78, 5
	s_cselect_b64 s[2:3], -1, 0
	s_and_b64 s[10:11], s[2:3], s[0:1]
	s_andn2_b64 vcc, exec, s[10:11]
	s_cbranch_vccnz .LBB0_613
	s_mov_b64 s[0:1], s[72:73]
	s_load_dwordx4 s[12:15], s[0:1], 0xe0
	v_mov_b32_e32 v0, v254
	s_lshl_b32 s2, s96, 3
	v_readfirstlane_b32 s0, v0
	s_ashr_i32 s0, s0, 6
	s_add_i32 s18, s0, s2
	s_cmp_gt_i32 s18, 0x17fff
	s_cbranch_scc1 .LBB0_467
	v_and_b32_e32 v66, 63, v254
	v_lshrrev_b32_e32 v64, 5, v66
	v_and_b32_e32 v66, 31, v66
	v_lshlrev_b32_e32 v65, 15, v64
	v_lshlrev_b32_e32 v64, 20, v64
	v_lshl_add_u32 v64, v66, 4, v64
	v_lshrrev_b32_e32 v66, 3, v66
	v_lshl_add_u32 v65, v66, 2, v65
	v_readfirstlane_b32 s16, v254
	s_nop 3
	s_lshl_b32 s17, s96, 3
	s_lshr_b32 s16, s16, 6
	s_add_i32 s16, s16, s17
	s_waitcnt lgkmcnt(0)
	s_mov_b64 s[6:7], s[14:15]
	s_lshl_b32 s17, s16, 9
	s_add_u32 s20, s6, s17
	s_addc_u32 s21, s7, 0
	s_add_u32 s20, s20, 0x2a000000
	s_addc_u32 s21, s21, 0
	s_add_u32 s24, s6, s17
	s_addc_u32 s25, s7, 0
	s_add_u32 s24, s24, 0x3c000000
	s_addc_u32 s25, s25, 0
	s_lshl_b32 s17, s16, 4
	s_add_u32 s22, s6, s17
	s_addc_u32 s23, s7, 0
	s_add_u32 s22, s22, 0x33000000
	s_addc_u32 s23, s23, 0
	s_mov_b64 s[26:27], s[20:21]
	global_load_dwordx4 v[0:3], v64, s[26:27]
	s_add_u32 s26, s20, 0x3000000
	s_addc_u32 s27, s21, 0
	global_load_dwordx4 v[4:7], v64, s[26:27]
	s_add_u32 s26, s20, 0x6000000
	s_addc_u32 s27, s21, 0
	global_load_dwordx4 v[8:11], v64, s[26:27]
	s_mov_b64 s[26:27], s[22:23]
	global_load_dword v12, v65, s[26:27]
	s_add_u32 s26, s22, 0x180000
	s_addc_u32 s27, s23, 0
	global_load_dword v13, v65, s[26:27]
	s_add_u32 s26, s22, 0x300000
	s_addc_u32 s27, s23, 0
	global_load_dword v14, v65, s[26:27]
	s_add_u32 s26, s20, 0x200000
	s_addc_u32 s27, s21, 0
	global_load_dwordx4 v[16:19], v64, s[26:27]
	s_add_u32 s26, s20, 0x3200000
	s_addc_u32 s27, s21, 0
	global_load_dwordx4 v[20:23], v64, s[26:27]
	s_add_u32 s26, s20, 0x6200000
	s_addc_u32 s27, s21, 0
	global_load_dwordx4 v[24:27], v64, s[26:27]
	s_add_u32 s26, s22, 0x10000
	s_addc_u32 s27, s23, 0
	global_load_dword v28, v65, s[26:27]
	s_add_u32 s26, s22, 0x190000
	s_addc_u32 s27, s23, 0
	global_load_dword v29, v65, s[26:27]
	s_add_u32 s26, s22, 0x310000
	s_addc_u32 s27, s23, 0
	global_load_dword v30, v65, s[26:27]
	s_add_u32 s26, s20, 0x400000
	s_addc_u32 s27, s21, 0
	global_load_dwordx4 v[32:35], v64, s[26:27]
	s_add_u32 s26, s20, 0x3400000
	s_addc_u32 s27, s21, 0
	global_load_dwordx4 v[36:39], v64, s[26:27]
	s_add_u32 s26, s20, 0x6400000
	s_addc_u32 s27, s21, 0
	global_load_dwordx4 v[40:43], v64, s[26:27]
	s_add_u32 s26, s22, 0x20000
	s_addc_u32 s27, s23, 0
	global_load_dword v44, v65, s[26:27]
	s_add_u32 s26, s22, 0x1a0000
	s_addc_u32 s27, s23, 0
	global_load_dword v45, v65, s[26:27]
	s_add_u32 s26, s22, 0x320000
	s_addc_u32 s27, s23, 0
	global_load_dword v46, v65, s[26:27]
	s_add_u32 s26, s20, 0x600000
	s_addc_u32 s27, s21, 0
	global_load_dwordx4 v[48:51], v64, s[26:27]
	s_add_u32 s26, s20, 0x3600000
	s_addc_u32 s27, s21, 0
	global_load_dwordx4 v[52:55], v64, s[26:27]
	s_add_u32 s26, s20, 0x6600000
	s_addc_u32 s27, s21, 0
	global_load_dwordx4 v[56:59], v64, s[26:27]
	s_add_u32 s26, s22, 0x30000
	s_addc_u32 s27, s23, 0
	global_load_dword v60, v65, s[26:27]
	s_add_u32 s26, s22, 0x1b0000
	s_addc_u32 s27, s23, 0
	global_load_dword v61, v65, s[26:27]
	s_add_u32 s26, s22, 0x330000
	s_addc_u32 s27, s23, 0
	global_load_dword v62, v65, s[26:27]
	s_waitcnt vmcnt(18)
	v_max3_f32 v68, v12, v13, v14
	v_sub_f32_e32 v69, v12, v68
	v_sub_f32_e32 v70, v13, v68
	v_sub_f32_e32 v71, v14, v68
	v_mul_f32_e32 v69, 0x3fb8aa3b, v69
	v_mul_f32_e32 v70, 0x3fb8aa3b, v70
	v_mul_f32_e32 v71, 0x3fb8aa3b, v71
	v_exp_f32_e32 v69, v69
	v_exp_f32_e32 v70, v70
	v_exp_f32_e32 v71, v71
	s_nop 0
	v_add_f32_e32 v72, v69, v70
	v_add_f32_e32 v72, v71, v72
	v_div_scale_f32 v73, s[28:29], v72, v72, 1.0
	v_rcp_f32_e32 v74, v73
	v_div_scale_f32 v75, vcc, 1.0, v72, 1.0
	s_nop 0
	v_fma_f32 v76, -v73, v74, 1.0
	v_fmac_f32_e32 v74, v76, v74
	v_mul_f32_e32 v77, v75, v74
	v_fma_f32 v76, -v73, v77, v75
	v_fmac_f32_e32 v77, v76, v74
	v_fma_f32 v73, -v73, v77, v75
	v_div_fmas_f32 v73, v73, v74, v77
	v_div_fixup_f32 v72, v73, v72, 1.0
	v_mul_f32_e32 v69, v69, v72
	v_mul_f32_e32 v70, v70, v72
	v_mul_f32_e32 v71, v71, v72
	v_lshlrev_b32_e32 v78, 16, v0
	v_and_b32_e32 v81, 0xffff0000, v0
	v_lshlrev_b32_e32 v79, 16, v4
	v_and_b32_e32 v82, 0xffff0000, v4
	v_lshlrev_b32_e32 v80, 16, v8
	v_and_b32_e32 v83, 0xffff0000, v8
	v_mul_f32_e32 v84, v69, v78
	v_mul_f32_e32 v85, v69, v81
	v_fmac_f32_e32 v84, v70, v79
	v_fmac_f32_e32 v85, v70, v82
	v_fmac_f32_e32 v84, v71, v80
	v_fmac_f32_e32 v85, v71, v83
	v_cvt_pk_bf16_f32 v96, v84, v85
	v_lshlrev_b32_e32 v78, 16, v1
	v_and_b32_e32 v81, 0xffff0000, v1
	v_lshlrev_b32_e32 v79, 16, v5
	v_and_b32_e32 v82, 0xffff0000, v5
	v_lshlrev_b32_e32 v80, 16, v9
	v_and_b32_e32 v83, 0xffff0000, v9
	v_mul_f32_e32 v84, v69, v78
	v_mul_f32_e32 v85, v69, v81
	v_fmac_f32_e32 v84, v70, v79
	v_fmac_f32_e32 v85, v70, v82
	v_fmac_f32_e32 v84, v71, v80
	v_fmac_f32_e32 v85, v71, v83
	v_cvt_pk_bf16_f32 v97, v84, v85
	v_lshlrev_b32_e32 v78, 16, v2
	v_and_b32_e32 v81, 0xffff0000, v2
	v_lshlrev_b32_e32 v79, 16, v6
	v_and_b32_e32 v82, 0xffff0000, v6
	v_lshlrev_b32_e32 v80, 16, v10
	v_and_b32_e32 v83, 0xffff0000, v10
	v_mul_f32_e32 v84, v69, v78
	v_mul_f32_e32 v85, v69, v81
	v_fmac_f32_e32 v84, v70, v79
	v_fmac_f32_e32 v85, v70, v82
	v_fmac_f32_e32 v84, v71, v80
	v_fmac_f32_e32 v85, v71, v83
	v_cvt_pk_bf16_f32 v98, v84, v85
	v_lshlrev_b32_e32 v78, 16, v3
	v_and_b32_e32 v81, 0xffff0000, v3
	v_lshlrev_b32_e32 v79, 16, v7
	v_and_b32_e32 v82, 0xffff0000, v7
	v_lshlrev_b32_e32 v80, 16, v11
	v_and_b32_e32 v83, 0xffff0000, v11
	v_mul_f32_e32 v84, v69, v78
	v_mul_f32_e32 v85, v69, v81
	v_fmac_f32_e32 v84, v70, v79
	v_fmac_f32_e32 v85, v70, v82
	v_fmac_f32_e32 v84, v71, v80
	v_fmac_f32_e32 v85, v71, v83
	v_cvt_pk_bf16_f32 v99, v84, v85
	s_mov_b64 s[26:27], s[24:25]
	global_store_dwordx4 v64, v[96:99], s[26:27]
	s_add_u32 s26, s20, 0x800000
	s_addc_u32 s27, s21, 0
	global_load_dwordx4 v[0:3], v64, s[26:27]
	s_add_u32 s26, s20, 0x3800000
	s_addc_u32 s27, s21, 0
	global_load_dwordx4 v[4:7], v64, s[26:27]
	s_add_u32 s26, s20, 0x6800000
	s_addc_u32 s27, s21, 0
	global_load_dwordx4 v[8:11], v64, s[26:27]
	s_add_u32 s26, s22, 0x40000
	s_addc_u32 s27, s23, 0
	global_load_dword v12, v65, s[26:27]
	s_add_u32 s26, s22, 0x1c0000
	s_addc_u32 s27, s23, 0
	global_load_dword v13, v65, s[26:27]
	s_add_u32 s26, s22, 0x340000
	s_addc_u32 s27, s23, 0
	global_load_dword v14, v65, s[26:27]
	s_waitcnt vmcnt(19)
; __device__ __forceinline__ float bf_lo(unsigned w) { return __uint_as_float(w << 16); }
; __device__ __forceinline__ float bf_hi(unsigned w) { return __uint_as_float(w & 0xffff0000u); }
; __device__ __forceinline__ unsigned pk2(float lo, float hi) { return pg8::cvt_pk_bf16(lo, hi); }
; __device__ __forceinline__ void merge_rows(const Args& a, int gw, int NGW, int lane) {
;     ...
;         for (int r = 0; r < 4; ++r) { const int m = mb + r * NGW; if (m < MT) {
;             const float mxl = fmaxf(l[r][0], fmaxf(l[r][1], l[r][2]));
;             float a0 = __expf(l[r][0] - mxl), a1 = __expf(l[r][1] - mxl), a2 = __expf(l[r][2] - mxl); const float is = 1.0f / (a0 + a1 + a2); a0 *= is; a1 *= is; a2 *= is;
;             const v2u o0 = o[r][0], o1 = o[r][1], o2 = o[r][2];
;             v2u w;
;             w.x = pk2(a0 * pg8::bf_lo(o0.x) + a1 * pg8::bf_lo(o1.x) + a2 * pg8::bf_lo(o2.x), a0 * pg8::bf_hi(o0.x) + a1 * pg8::bf_hi(o1.x) + a2 * pg8::bf_hi(o2.x));
;             w.y = pk2(a0 * pg8::bf_lo(o0.y) + a1 * pg8::bf_lo(o1.y) + a2 * pg8::bf_lo(o2.y), a0 * pg8::bf_hi(o0.y) + a1 * pg8::bf_hi(o1.y) + a2 * pg8::bf_hi(o2.y));
;             *(v2u*)(YAT + (size_t)m * 256 + 4 * lane) = w; } }
	v_max3_f32 v68, v28, v29, v30
	v_sub_f32_e32 v69, v28, v68
	v_sub_f32_e32 v70, v29, v68
	v_sub_f32_e32 v71, v30, v68
	v_mul_f32_e32 v69, 0x3fb8aa3b, v69
	v_mul_f32_e32 v70, 0x3fb8aa3b, v70
	v_mul_f32_e32 v71, 0x3fb8aa3b, v71
	v_exp_f32_e32 v69, v69
	v_exp_f32_e32 v70, v70
	v_exp_f32_e32 v71, v71
	s_nop 0
	v_add_f32_e32 v72, v69, v70
	v_add_f32_e32 v72, v71, v72
	v_div_scale_f32 v73, s[28:29], v72, v72, 1.0
	v_rcp_f32_e32 v74, v73
	v_div_scale_f32 v75, vcc, 1.0, v72, 1.0
	s_nop 0
	v_fma_f32 v76, -v73, v74, 1.0
	v_fmac_f32_e32 v74, v76, v74
	v_mul_f32_e32 v77, v75, v74
	v_fma_f32 v76, -v73, v77, v75
	v_fmac_f32_e32 v77, v76, v74
	v_fma_f32 v73, -v73, v77, v75
	v_div_fmas_f32 v73, v73, v74, v77
	v_div_fixup_f32 v72, v73, v72, 1.0
	v_mul_f32_e32 v69, v69, v72
	v_mul_f32_e32 v70, v70, v72
	v_mul_f32_e32 v71, v71, v72
	v_lshlrev_b32_e32 v78, 16, v16
	v_and_b32_e32 v81, 0xffff0000, v16
	v_lshlrev_b32_e32 v79, 16, v20
	v_and_b32_e32 v82, 0xffff0000, v20
	v_lshlrev_b32_e32 v80, 16, v24
	v_and_b32_e32 v83, 0xffff0000, v24
	v_mul_f32_e32 v84, v69, v78
	v_mul_f32_e32 v85, v69, v81
	v_fmac_f32_e32 v84, v70, v79
	v_fmac_f32_e32 v85, v70, v82
	v_fmac_f32_e32 v84, v71, v80
	v_fmac_f32_e32 v85, v71, v83
	v_cvt_pk_bf16_f32 v100, v84, v85
	v_lshlrev_b32_e32 v78, 16, v17
	v_and_b32_e32 v81, 0xffff0000, v17
	v_lshlrev_b32_e32 v79, 16, v21
	v_and_b32_e32 v82, 0xffff0000, v21
	v_lshlrev_b32_e32 v80, 16, v25
	v_and_b32_e32 v83, 0xffff0000, v25
	v_mul_f32_e32 v84, v69, v78
	v_mul_f32_e32 v85, v69, v81
	v_fmac_f32_e32 v84, v70, v79
	v_fmac_f32_e32 v85, v70, v82
	v_fmac_f32_e32 v84, v71, v80
	v_fmac_f32_e32 v85, v71, v83
	v_cvt_pk_bf16_f32 v101, v84, v85
	v_lshlrev_b32_e32 v78, 16, v18
	v_and_b32_e32 v81, 0xffff0000, v18
	v_lshlrev_b32_e32 v79, 16, v22
	v_and_b32_e32 v82, 0xffff0000, v22
	v_lshlrev_b32_e32 v80, 16, v26
	v_and_b32_e32 v83, 0xffff0000, v26
	v_mul_f32_e32 v84, v69, v78
	v_mul_f32_e32 v85, v69, v81
	v_fmac_f32_e32 v84, v70, v79
	v_fmac_f32_e32 v85, v70, v82
	v_fmac_f32_e32 v84, v71, v80
	v_fmac_f32_e32 v85, v71, v83
	v_cvt_pk_bf16_f32 v102, v84, v85
	v_lshlrev_b32_e32 v78, 16, v19
	v_and_b32_e32 v81, 0xffff0000, v19
	v_lshlrev_b32_e32 v79, 16, v23
	v_and_b32_e32 v82, 0xffff0000, v23
	v_lshlrev_b32_e32 v80, 16, v27
	v_and_b32_e32 v83, 0xffff0000, v27
	v_mul_f32_e32 v84, v69, v78
	v_mul_f32_e32 v85, v69, v81
	v_fmac_f32_e32 v84, v70, v79
	v_fmac_f32_e32 v85, v70, v82
	v_fmac_f32_e32 v84, v71, v80
	v_fmac_f32_e32 v85, v71, v83
	v_cvt_pk_bf16_f32 v103, v84, v85
	s_add_u32 s26, s24, 0x200000
	s_addc_u32 s27, s25, 0
	global_store_dwordx4 v64, v[100:103], s[26:27]
	s_add_u32 s26, s20, 0xa00000
	s_addc_u32 s27, s21, 0
	global_load_dwordx4 v[16:19], v64, s[26:27]
	s_add_u32 s26, s20, 0x3a00000
	s_addc_u32 s27, s21, 0
	global_load_dwordx4 v[20:23], v64, s[26:27]
	s_add_u32 s26, s20, 0x6a00000
	s_addc_u32 s27, s21, 0
	global_load_dwordx4 v[24:27], v64, s[26:27]
	s_add_u32 s26, s22, 0x50000
	s_addc_u32 s27, s23, 0
	global_load_dword v28, v65, s[26:27]
	s_add_u32 s26, s22, 0x1d0000
	s_addc_u32 s27, s23, 0
	global_load_dword v29, v65, s[26:27]
	s_add_u32 s26, s22, 0x350000
	s_addc_u32 s27, s23, 0
	global_load_dword v30, v65, s[26:27]
	s_waitcnt vmcnt(20)
	v_max3_f32 v68, v44, v45, v46
	v_sub_f32_e32 v69, v44, v68
	v_sub_f32_e32 v70, v45, v68
	v_sub_f32_e32 v71, v46, v68
	v_mul_f32_e32 v69, 0x3fb8aa3b, v69
	v_mul_f32_e32 v70, 0x3fb8aa3b, v70
	v_mul_f32_e32 v71, 0x3fb8aa3b, v71
	v_exp_f32_e32 v69, v69
	v_exp_f32_e32 v70, v70
	v_exp_f32_e32 v71, v71
	s_nop 0
	v_add_f32_e32 v72, v69, v70
	v_add_f32_e32 v72, v71, v72
	v_div_scale_f32 v73, s[28:29], v72, v72, 1.0
	v_rcp_f32_e32 v74, v73
	v_div_scale_f32 v75, vcc, 1.0, v72, 1.0
	s_nop 0
	v_fma_f32 v76, -v73, v74, 1.0
	v_fmac_f32_e32 v74, v76, v74
	v_mul_f32_e32 v77, v75, v74
	v_fma_f32 v76, -v73, v77, v75
	v_fmac_f32_e32 v77, v76, v74
	v_fma_f32 v73, -v73, v77, v75
	v_div_fmas_f32 v73, v73, v74, v77
	v_div_fixup_f32 v72, v73, v72, 1.0
	v_mul_f32_e32 v69, v69, v72
	v_mul_f32_e32 v70, v70, v72
	v_mul_f32_e32 v71, v71, v72
	v_lshlrev_b32_e32 v78, 16, v32
	v_and_b32_e32 v81, 0xffff0000, v32
	v_lshlrev_b32_e32 v79, 16, v36
	v_and_b32_e32 v82, 0xffff0000, v36
	v_lshlrev_b32_e32 v80, 16, v40
	v_and_b32_e32 v83, 0xffff0000, v40
	v_mul_f32_e32 v84, v69, v78
	v_mul_f32_e32 v85, v69, v81
	v_fmac_f32_e32 v84, v70, v79
	v_fmac_f32_e32 v85, v70, v82
	v_fmac_f32_e32 v84, v71, v80
	v_fmac_f32_e32 v85, v71, v83
	v_cvt_pk_bf16_f32 v96, v84, v85
	v_lshlrev_b32_e32 v78, 16, v33
	v_and_b32_e32 v81, 0xffff0000, v33
	v_lshlrev_b32_e32 v79, 16, v37
	v_and_b32_e32 v82, 0xffff0000, v37
	v_lshlrev_b32_e32 v80, 16, v41
	v_and_b32_e32 v83, 0xffff0000, v41
	v_mul_f32_e32 v84, v69, v78
	v_mul_f32_e32 v85, v69, v81
	v_fmac_f32_e32 v84, v70, v79
	v_fmac_f32_e32 v85, v70, v82
	v_fmac_f32_e32 v84, v71, v80
	v_fmac_f32_e32 v85, v71, v83
	v_cvt_pk_bf16_f32 v97, v84, v85
	v_lshlrev_b32_e32 v78, 16, v34
	v_and_b32_e32 v81, 0xffff0000, v34
	v_lshlrev_b32_e32 v79, 16, v38
	v_and_b32_e32 v82, 0xffff0000, v38
	v_lshlrev_b32_e32 v80, 16, v42
	v_and_b32_e32 v83, 0xffff0000, v42
	v_mul_f32_e32 v84, v69, v78
	v_mul_f32_e32 v85, v69, v81
	v_fmac_f32_e32 v84, v70, v79
	v_fmac_f32_e32 v85, v70, v82
	v_fmac_f32_e32 v84, v71, v80
	v_fmac_f32_e32 v85, v71, v83
	v_cvt_pk_bf16_f32 v98, v84, v85
	v_lshlrev_b32_e32 v78, 16, v35
	v_and_b32_e32 v81, 0xffff0000, v35
	v_lshlrev_b32_e32 v79, 16, v39
	v_and_b32_e32 v82, 0xffff0000, v39
	v_lshlrev_b32_e32 v80, 16, v43
	v_and_b32_e32 v83, 0xffff0000, v43
	v_mul_f32_e32 v84, v69, v78
	v_mul_f32_e32 v85, v69, v81
	v_fmac_f32_e32 v84, v70, v79
	v_fmac_f32_e32 v85, v70, v82
	v_fmac_f32_e32 v84, v71, v80
	v_fmac_f32_e32 v85, v71, v83
	v_cvt_pk_bf16_f32 v99, v84, v85
	s_add_u32 s26, s24, 0x400000
	s_addc_u32 s27, s25, 0
	global_store_dwordx4 v64, v[96:99], s[26:27]
	s_add_u32 s26, s20, 0xc00000
	s_addc_u32 s27, s21, 0
	global_load_dwordx4 v[32:35], v64, s[26:27]
	s_add_u32 s26, s20, 0x3c00000
	s_addc_u32 s27, s21, 0
	global_load_dwordx4 v[36:39], v64, s[26:27]
	s_add_u32 s26, s20, 0x6c00000
	s_addc_u32 s27, s21, 0
	global_load_dwordx4 v[40:43], v64, s[26:27]
	s_add_u32 s26, s22, 0x60000
	s_addc_u32 s27, s23, 0
	global_load_dword v44, v65, s[26:27]
	s_add_u32 s26, s22, 0x1e0000
	s_addc_u32 s27, s23, 0
	global_load_dword v45, v65, s[26:27]
	s_add_u32 s26, s22, 0x360000
	s_addc_u32 s27, s23, 0
	global_load_dword v46, v65, s[26:27]
	s_waitcnt vmcnt(21)
; __device__ __forceinline__ float bf_lo(unsigned w) { return __uint_as_float(w << 16); }
; __device__ __forceinline__ float bf_hi(unsigned w) { return __uint_as_float(w & 0xffff0000u); }
; __device__ __forceinline__ unsigned pk2(float lo, float hi) { return pg8::cvt_pk_bf16(lo, hi); }
; __device__ __forceinline__ void merge_rows(const Args& a, int gw, int NGW, int lane) {
;     ...
;         for (int r = 0; r < 4; ++r) { const int m = mb + r * NGW; if (m < MT) {
;             const float mxl = fmaxf(l[r][0], fmaxf(l[r][1], l[r][2]));
;             float a0 = __expf(l[r][0] - mxl), a1 = __expf(l[r][1] - mxl), a2 = __expf(l[r][2] - mxl); const float is = 1.0f / (a0 + a1 + a2); a0 *= is; a1 *= is; a2 *= is;
;             const v2u o0 = o[r][0], o1 = o[r][1], o2 = o[r][2];
;             v2u w;
;             w.x = pk2(a0 * pg8::bf_lo(o0.x) + a1 * pg8::bf_lo(o1.x) + a2 * pg8::bf_lo(o2.x), a0 * pg8::bf_hi(o0.x) + a1 * pg8::bf_hi(o1.x) + a2 * pg8::bf_hi(o2.x));
;             w.y = pk2(a0 * pg8::bf_lo(o0.y) + a1 * pg8::bf_lo(o1.y) + a2 * pg8::bf_lo(o2.y), a0 * pg8::bf_hi(o0.y) + a1 * pg8::bf_hi(o1.y) + a2 * pg8::bf_hi(o2.y));
;             *(v2u*)(YAT + (size_t)m * 256 + 4 * lane) = w; } }
	v_max3_f32 v68, v60, v61, v62
	v_sub_f32_e32 v69, v60, v68
	v_sub_f32_e32 v70, v61, v68
	v_sub_f32_e32 v71, v62, v68
	v_mul_f32_e32 v69, 0x3fb8aa3b, v69
	v_mul_f32_e32 v70, 0x3fb8aa3b, v70
	v_mul_f32_e32 v71, 0x3fb8aa3b, v71
	v_exp_f32_e32 v69, v69
	v_exp_f32_e32 v70, v70
	v_exp_f32_e32 v71, v71
	s_nop 0
	v_add_f32_e32 v72, v69, v70
	v_add_f32_e32 v72, v71, v72
	v_div_scale_f32 v73, s[28:29], v72, v72, 1.0
	v_rcp_f32_e32 v74, v73
	v_div_scale_f32 v75, vcc, 1.0, v72, 1.0
	s_nop 0
	v_fma_f32 v76, -v73, v74, 1.0
	v_fmac_f32_e32 v74, v76, v74
	v_mul_f32_e32 v77, v75, v74
	v_fma_f32 v76, -v73, v77, v75
	v_fmac_f32_e32 v77, v76, v74
	v_fma_f32 v73, -v73, v77, v75
	v_div_fmas_f32 v73, v73, v74, v77
	v_div_fixup_f32 v72, v73, v72, 1.0
	v_mul_f32_e32 v69, v69, v72
	v_mul_f32_e32 v70, v70, v72
	v_mul_f32_e32 v71, v71, v72
	v_lshlrev_b32_e32 v78, 16, v48
	v_and_b32_e32 v81, 0xffff0000, v48
	v_lshlrev_b32_e32 v79, 16, v52
	v_and_b32_e32 v82, 0xffff0000, v52
	v_lshlrev_b32_e32 v80, 16, v56
	v_and_b32_e32 v83, 0xffff0000, v56
	v_mul_f32_e32 v84, v69, v78
	v_mul_f32_e32 v85, v69, v81
	v_fmac_f32_e32 v84, v70, v79
	v_fmac_f32_e32 v85, v70, v82
	v_fmac_f32_e32 v84, v71, v80
	v_fmac_f32_e32 v85, v71, v83
	v_cvt_pk_bf16_f32 v100, v84, v85
	v_lshlrev_b32_e32 v78, 16, v49
	v_and_b32_e32 v81, 0xffff0000, v49
	v_lshlrev_b32_e32 v79, 16, v53
	v_and_b32_e32 v82, 0xffff0000, v53
	v_lshlrev_b32_e32 v80, 16, v57
	v_and_b32_e32 v83, 0xffff0000, v57
	v_mul_f32_e32 v84, v69, v78
	v_mul_f32_e32 v85, v69, v81
	v_fmac_f32_e32 v84, v70, v79
	v_fmac_f32_e32 v85, v70, v82
	v_fmac_f32_e32 v84, v71, v80
	v_fmac_f32_e32 v85, v71, v83
	v_cvt_pk_bf16_f32 v101, v84, v85
	v_lshlrev_b32_e32 v78, 16, v50
	v_and_b32_e32 v81, 0xffff0000, v50
	v_lshlrev_b32_e32 v79, 16, v54
	v_and_b32_e32 v82, 0xffff0000, v54
	v_lshlrev_b32_e32 v80, 16, v58
	v_and_b32_e32 v83, 0xffff0000, v58
	v_mul_f32_e32 v84, v69, v78
	v_mul_f32_e32 v85, v69, v81
	v_fmac_f32_e32 v84, v70, v79
	v_fmac_f32_e32 v85, v70, v82
	v_fmac_f32_e32 v84, v71, v80
	v_fmac_f32_e32 v85, v71, v83
	v_cvt_pk_bf16_f32 v102, v84, v85
	v_lshlrev_b32_e32 v78, 16, v51
	v_and_b32_e32 v81, 0xffff0000, v51
	v_lshlrev_b32_e32 v79, 16, v55
	v_and_b32_e32 v82, 0xffff0000, v55
	v_lshlrev_b32_e32 v80, 16, v59
	v_and_b32_e32 v83, 0xffff0000, v59
	v_mul_f32_e32 v84, v69, v78
	v_mul_f32_e32 v85, v69, v81
	v_fmac_f32_e32 v84, v70, v79
	v_fmac_f32_e32 v85, v70, v82
	v_fmac_f32_e32 v84, v71, v80
	v_fmac_f32_e32 v85, v71, v83
	v_cvt_pk_bf16_f32 v103, v84, v85
	s_add_u32 s26, s24, 0x600000
	s_addc_u32 s27, s25, 0
	global_store_dwordx4 v64, v[100:103], s[26:27]
	s_add_u32 s26, s20, 0xe00000
	s_addc_u32 s27, s21, 0
	global_load_dwordx4 v[48:51], v64, s[26:27]
	s_add_u32 s26, s20, 0x3e00000
	s_addc_u32 s27, s21, 0
	global_load_dwordx4 v[52:55], v64, s[26:27]
	s_add_u32 s26, s20, 0x6e00000
	s_addc_u32 s27, s21, 0
	global_load_dwordx4 v[56:59], v64, s[26:27]
	s_add_u32 s26, s22, 0x70000
	s_addc_u32 s27, s23, 0
	global_load_dword v60, v65, s[26:27]
	s_add_u32 s26, s22, 0x1f0000
	s_addc_u32 s27, s23, 0
	global_load_dword v61, v65, s[26:27]
	s_add_u32 s26, s22, 0x370000
	s_addc_u32 s27, s23, 0
	global_load_dword v62, v65, s[26:27]
	s_waitcnt vmcnt(21)
	v_max3_f32 v68, v12, v13, v14
	v_sub_f32_e32 v69, v12, v68
	v_sub_f32_e32 v70, v13, v68
	v_sub_f32_e32 v71, v14, v68
	v_mul_f32_e32 v69, 0x3fb8aa3b, v69
	v_mul_f32_e32 v70, 0x3fb8aa3b, v70
	v_mul_f32_e32 v71, 0x3fb8aa3b, v71
	v_exp_f32_e32 v69, v69
	v_exp_f32_e32 v70, v70
	v_exp_f32_e32 v71, v71
	s_nop 0
	v_add_f32_e32 v72, v69, v70
	v_add_f32_e32 v72, v71, v72
	v_div_scale_f32 v73, s[28:29], v72, v72, 1.0
	v_rcp_f32_e32 v74, v73
	v_div_scale_f32 v75, vcc, 1.0, v72, 1.0
	s_nop 0
	v_fma_f32 v76, -v73, v74, 1.0
	v_fmac_f32_e32 v74, v76, v74
	v_mul_f32_e32 v77, v75, v74
	v_fma_f32 v76, -v73, v77, v75
	v_fmac_f32_e32 v77, v76, v74
	v_fma_f32 v73, -v73, v77, v75
	v_div_fmas_f32 v73, v73, v74, v77
	v_div_fixup_f32 v72, v73, v72, 1.0
	v_mul_f32_e32 v69, v69, v72
	v_mul_f32_e32 v70, v70, v72
	v_mul_f32_e32 v71, v71, v72
	v_lshlrev_b32_e32 v78, 16, v0
	v_and_b32_e32 v81, 0xffff0000, v0
	v_lshlrev_b32_e32 v79, 16, v4
	v_and_b32_e32 v82, 0xffff0000, v4
	v_lshlrev_b32_e32 v80, 16, v8
	v_and_b32_e32 v83, 0xffff0000, v8
	v_mul_f32_e32 v84, v69, v78
	v_mul_f32_e32 v85, v69, v81
	v_fmac_f32_e32 v84, v70, v79
	v_fmac_f32_e32 v85, v70, v82
	v_fmac_f32_e32 v84, v71, v80
	v_fmac_f32_e32 v85, v71, v83
	v_cvt_pk_bf16_f32 v96, v84, v85
	v_lshlrev_b32_e32 v78, 16, v1
	v_and_b32_e32 v81, 0xffff0000, v1
	v_lshlrev_b32_e32 v79, 16, v5
	v_and_b32_e32 v82, 0xffff0000, v5
	v_lshlrev_b32_e32 v80, 16, v9
	v_and_b32_e32 v83, 0xffff0000, v9
	v_mul_f32_e32 v84, v69, v78
	v_mul_f32_e32 v85, v69, v81
	v_fmac_f32_e32 v84, v70, v79
	v_fmac_f32_e32 v85, v70, v82
	v_fmac_f32_e32 v84, v71, v80
	v_fmac_f32_e32 v85, v71, v83
	v_cvt_pk_bf16_f32 v97, v84, v85
	v_lshlrev_b32_e32 v78, 16, v2
	v_and_b32_e32 v81, 0xffff0000, v2
	v_lshlrev_b32_e32 v79, 16, v6
	v_and_b32_e32 v82, 0xffff0000, v6
	v_lshlrev_b32_e32 v80, 16, v10
	v_and_b32_e32 v83, 0xffff0000, v10
	v_mul_f32_e32 v84, v69, v78
	v_mul_f32_e32 v85, v69, v81
	v_fmac_f32_e32 v84, v70, v79
	v_fmac_f32_e32 v85, v70, v82
	v_fmac_f32_e32 v84, v71, v80
	v_fmac_f32_e32 v85, v71, v83
	v_cvt_pk_bf16_f32 v98, v84, v85
	v_lshlrev_b32_e32 v78, 16, v3
	v_and_b32_e32 v81, 0xffff0000, v3
	v_lshlrev_b32_e32 v79, 16, v7
	v_and_b32_e32 v82, 0xffff0000, v7
	v_lshlrev_b32_e32 v80, 16, v11
	v_and_b32_e32 v83, 0xffff0000, v11
	v_mul_f32_e32 v84, v69, v78
	v_mul_f32_e32 v85, v69, v81
	v_fmac_f32_e32 v84, v70, v79
	v_fmac_f32_e32 v85, v70, v82
	v_fmac_f32_e32 v84, v71, v80
	v_fmac_f32_e32 v85, v71, v83
	v_cvt_pk_bf16_f32 v99, v84, v85
	s_add_u32 s26, s24, 0x800000
	s_addc_u32 s27, s25, 0
	global_store_dwordx4 v64, v[96:99], s[26:27]
	s_add_u32 s26, s20, 0x1000000
	s_addc_u32 s27, s21, 0
	global_load_dwordx4 v[0:3], v64, s[26:27]
	s_add_u32 s26, s20, 0x4000000
	s_addc_u32 s27, s21, 0
	global_load_dwordx4 v[4:7], v64, s[26:27]
	s_add_u32 s26, s20, 0x7000000
	s_addc_u32 s27, s21, 0
	global_load_dwordx4 v[8:11], v64, s[26:27]
	s_add_u32 s26, s22, 0x80000
	s_addc_u32 s27, s23, 0
	global_load_dword v12, v65, s[26:27]
	s_add_u32 s26, s22, 0x200000
	s_addc_u32 s27, s23, 0
	global_load_dword v13, v65, s[26:27]
	s_add_u32 s26, s22, 0x380000
	s_addc_u32 s27, s23, 0
	global_load_dword v14, v65, s[26:27]
	s_waitcnt vmcnt(21)
; __device__ __forceinline__ float bf_lo(unsigned w) { return __uint_as_float(w << 16); }
; __device__ __forceinline__ float bf_hi(unsigned w) { return __uint_as_float(w & 0xffff0000u); }
; __device__ __forceinline__ unsigned pk2(float lo, float hi) { return pg8::cvt_pk_bf16(lo, hi); }
; __device__ __forceinline__ void merge_rows(const Args& a, int gw, int NGW, int lane) {
;     ...
;         for (int r = 0; r < 4; ++r) { const int m = mb + r * NGW; if (m < MT) {
;             const float mxl = fmaxf(l[r][0], fmaxf(l[r][1], l[r][2]));
;             float a0 = __expf(l[r][0] - mxl), a1 = __expf(l[r][1] - mxl), a2 = __expf(l[r][2] - mxl); const float is = 1.0f / (a0 + a1 + a2); a0 *= is; a1 *= is; a2 *= is;
;             const v2u o0 = o[r][0], o1 = o[r][1], o2 = o[r][2];
;             v2u w;
;             w.x = pk2(a0 * pg8::bf_lo(o0.x) + a1 * pg8::bf_lo(o1.x) + a2 * pg8::bf_lo(o2.x), a0 * pg8::bf_hi(o0.x) + a1 * pg8::bf_hi(o1.x) + a2 * pg8::bf_hi(o2.x));
;             w.y = pk2(a0 * pg8::bf_lo(o0.y) + a1 * pg8::bf_lo(o1.y) + a2 * pg8::bf_lo(o2.y), a0 * pg8::bf_hi(o0.y) + a1 * pg8::bf_hi(o1.y) + a2 * pg8::bf_hi(o2.y));
;             *(v2u*)(YAT + (size_t)m * 256 + 4 * lane) = w; } }
	v_max3_f32 v68, v28, v29, v30
	v_sub_f32_e32 v69, v28, v68
	v_sub_f32_e32 v70, v29, v68
	v_sub_f32_e32 v71, v30, v68
	v_mul_f32_e32 v69, 0x3fb8aa3b, v69
	v_mul_f32_e32 v70, 0x3fb8aa3b, v70
	v_mul_f32_e32 v71, 0x3fb8aa3b, v71
	v_exp_f32_e32 v69, v69
	v_exp_f32_e32 v70, v70
	v_exp_f32_e32 v71, v71
	s_nop 0
	v_add_f32_e32 v72, v69, v70
	v_add_f32_e32 v72, v71, v72
	v_div_scale_f32 v73, s[28:29], v72, v72, 1.0
	v_rcp_f32_e32 v74, v73
	v_div_scale_f32 v75, vcc, 1.0, v72, 1.0
	s_nop 0
	v_fma_f32 v76, -v73, v74, 1.0
	v_fmac_f32_e32 v74, v76, v74
	v_mul_f32_e32 v77, v75, v74
	v_fma_f32 v76, -v73, v77, v75
	v_fmac_f32_e32 v77, v76, v74
	v_fma_f32 v73, -v73, v77, v75
	v_div_fmas_f32 v73, v73, v74, v77
	v_div_fixup_f32 v72, v73, v72, 1.0
	v_mul_f32_e32 v69, v69, v72
	v_mul_f32_e32 v70, v70, v72
	v_mul_f32_e32 v71, v71, v72
	v_lshlrev_b32_e32 v78, 16, v16
	v_and_b32_e32 v81, 0xffff0000, v16
	v_lshlrev_b32_e32 v79, 16, v20
	v_and_b32_e32 v82, 0xffff0000, v20
	v_lshlrev_b32_e32 v80, 16, v24
	v_and_b32_e32 v83, 0xffff0000, v24
	v_mul_f32_e32 v84, v69, v78
	v_mul_f32_e32 v85, v69, v81
	v_fmac_f32_e32 v84, v70, v79
	v_fmac_f32_e32 v85, v70, v82
	v_fmac_f32_e32 v84, v71, v80
	v_fmac_f32_e32 v85, v71, v83
	v_cvt_pk_bf16_f32 v100, v84, v85
	v_lshlrev_b32_e32 v78, 16, v17
	v_and_b32_e32 v81, 0xffff0000, v17
	v_lshlrev_b32_e32 v79, 16, v21
	v_and_b32_e32 v82, 0xffff0000, v21
	v_lshlrev_b32_e32 v80, 16, v25
	v_and_b32_e32 v83, 0xffff0000, v25
	v_mul_f32_e32 v84, v69, v78
	v_mul_f32_e32 v85, v69, v81
	v_fmac_f32_e32 v84, v70, v79
	v_fmac_f32_e32 v85, v70, v82
	v_fmac_f32_e32 v84, v71, v80
	v_fmac_f32_e32 v85, v71, v83
	v_cvt_pk_bf16_f32 v101, v84, v85
	v_lshlrev_b32_e32 v78, 16, v18
	v_and_b32_e32 v81, 0xffff0000, v18
	v_lshlrev_b32_e32 v79, 16, v22
	v_and_b32_e32 v82, 0xffff0000, v22
	v_lshlrev_b32_e32 v80, 16, v26
	v_and_b32_e32 v83, 0xffff0000, v26
	v_mul_f32_e32 v84, v69, v78
	v_mul_f32_e32 v85, v69, v81
	v_fmac_f32_e32 v84, v70, v79
	v_fmac_f32_e32 v85, v70, v82
	v_fmac_f32_e32 v84, v71, v80
	v_fmac_f32_e32 v85, v71, v83
	v_cvt_pk_bf16_f32 v102, v84, v85
	v_lshlrev_b32_e32 v78, 16, v19
	v_and_b32_e32 v81, 0xffff0000, v19
	v_lshlrev_b32_e32 v79, 16, v23
	v_and_b32_e32 v82, 0xffff0000, v23
	v_lshlrev_b32_e32 v80, 16, v27
	v_and_b32_e32 v83, 0xffff0000, v27
	v_mul_f32_e32 v84, v69, v78
	v_mul_f32_e32 v85, v69, v81
	v_fmac_f32_e32 v84, v70, v79
	v_fmac_f32_e32 v85, v70, v82
	v_fmac_f32_e32 v84, v71, v80
	v_fmac_f32_e32 v85, v71, v83
	v_cvt_pk_bf16_f32 v103, v84, v85
	s_add_u32 s26, s24, 0xa00000
	s_addc_u32 s27, s25, 0
	global_store_dwordx4 v64, v[100:103], s[26:27]
	s_add_u32 s26, s20, 0x1200000
	s_addc_u32 s27, s21, 0
	global_load_dwordx4 v[16:19], v64, s[26:27]
	s_add_u32 s26, s20, 0x4200000
	s_addc_u32 s27, s21, 0
	global_load_dwordx4 v[20:23], v64, s[26:27]
	s_add_u32 s26, s20, 0x7200000
	s_addc_u32 s27, s21, 0
	global_load_dwordx4 v[24:27], v64, s[26:27]
	s_add_u32 s26, s22, 0x90000
	s_addc_u32 s27, s23, 0
	global_load_dword v28, v65, s[26:27]
	s_add_u32 s26, s22, 0x210000
	s_addc_u32 s27, s23, 0
	global_load_dword v29, v65, s[26:27]
	s_add_u32 s26, s22, 0x390000
	s_addc_u32 s27, s23, 0
	global_load_dword v30, v65, s[26:27]
	s_waitcnt vmcnt(21)
	v_max3_f32 v68, v44, v45, v46
	v_sub_f32_e32 v69, v44, v68
	v_sub_f32_e32 v70, v45, v68
	v_sub_f32_e32 v71, v46, v68
	v_mul_f32_e32 v69, 0x3fb8aa3b, v69
	v_mul_f32_e32 v70, 0x3fb8aa3b, v70
	v_mul_f32_e32 v71, 0x3fb8aa3b, v71
	v_exp_f32_e32 v69, v69
	v_exp_f32_e32 v70, v70
	v_exp_f32_e32 v71, v71
	s_nop 0
	v_add_f32_e32 v72, v69, v70
	v_add_f32_e32 v72, v71, v72
	v_div_scale_f32 v73, s[28:29], v72, v72, 1.0
	v_rcp_f32_e32 v74, v73
	v_div_scale_f32 v75, vcc, 1.0, v72, 1.0
	s_nop 0
	v_fma_f32 v76, -v73, v74, 1.0
	v_fmac_f32_e32 v74, v76, v74
	v_mul_f32_e32 v77, v75, v74
	v_fma_f32 v76, -v73, v77, v75
	v_fmac_f32_e32 v77, v76, v74
	v_fma_f32 v73, -v73, v77, v75
	v_div_fmas_f32 v73, v73, v74, v77
	v_div_fixup_f32 v72, v73, v72, 1.0
	v_mul_f32_e32 v69, v69, v72
	v_mul_f32_e32 v70, v70, v72
	v_mul_f32_e32 v71, v71, v72
	v_lshlrev_b32_e32 v78, 16, v32
	v_and_b32_e32 v81, 0xffff0000, v32
	v_lshlrev_b32_e32 v79, 16, v36
	v_and_b32_e32 v82, 0xffff0000, v36
	v_lshlrev_b32_e32 v80, 16, v40
	v_and_b32_e32 v83, 0xffff0000, v40
	v_mul_f32_e32 v84, v69, v78
	v_mul_f32_e32 v85, v69, v81
	v_fmac_f32_e32 v84, v70, v79
	v_fmac_f32_e32 v85, v70, v82
	v_fmac_f32_e32 v84, v71, v80
	v_fmac_f32_e32 v85, v71, v83
	v_cvt_pk_bf16_f32 v96, v84, v85
	v_lshlrev_b32_e32 v78, 16, v33
	v_and_b32_e32 v81, 0xffff0000, v33
	v_lshlrev_b32_e32 v79, 16, v37
	v_and_b32_e32 v82, 0xffff0000, v37
	v_lshlrev_b32_e32 v80, 16, v41
	v_and_b32_e32 v83, 0xffff0000, v41
	v_mul_f32_e32 v84, v69, v78
	v_mul_f32_e32 v85, v69, v81
	v_fmac_f32_e32 v84, v70, v79
	v_fmac_f32_e32 v85, v70, v82
	v_fmac_f32_e32 v84, v71, v80
	v_fmac_f32_e32 v85, v71, v83
	v_cvt_pk_bf16_f32 v97, v84, v85
	v_lshlrev_b32_e32 v78, 16, v34
	v_and_b32_e32 v81, 0xffff0000, v34
	v_lshlrev_b32_e32 v79, 16, v38
	v_and_b32_e32 v82, 0xffff0000, v38
	v_lshlrev_b32_e32 v80, 16, v42
	v_and_b32_e32 v83, 0xffff0000, v42
	v_mul_f32_e32 v84, v69, v78
	v_mul_f32_e32 v85, v69, v81
	v_fmac_f32_e32 v84, v70, v79
	v_fmac_f32_e32 v85, v70, v82
	v_fmac_f32_e32 v84, v71, v80
	v_fmac_f32_e32 v85, v71, v83
	v_cvt_pk_bf16_f32 v98, v84, v85
	v_lshlrev_b32_e32 v78, 16, v35
	v_and_b32_e32 v81, 0xffff0000, v35
	v_lshlrev_b32_e32 v79, 16, v39
	v_and_b32_e32 v82, 0xffff0000, v39
	v_lshlrev_b32_e32 v80, 16, v43
	v_and_b32_e32 v83, 0xffff0000, v43
	v_mul_f32_e32 v84, v69, v78
	v_mul_f32_e32 v85, v69, v81
	v_fmac_f32_e32 v84, v70, v79
	v_fmac_f32_e32 v85, v70, v82
	v_fmac_f32_e32 v84, v71, v80
	v_fmac_f32_e32 v85, v71, v83
	v_cvt_pk_bf16_f32 v99, v84, v85
	s_add_u32 s26, s24, 0xc00000
	s_addc_u32 s27, s25, 0
	global_store_dwordx4 v64, v[96:99], s[26:27]
	s_add_u32 s26, s20, 0x1400000
	s_addc_u32 s27, s21, 0
	global_load_dwordx4 v[32:35], v64, s[26:27]
	s_add_u32 s26, s20, 0x4400000
	s_addc_u32 s27, s21, 0
	global_load_dwordx4 v[36:39], v64, s[26:27]
	s_add_u32 s26, s20, 0x7400000
	s_addc_u32 s27, s21, 0
	global_load_dwordx4 v[40:43], v64, s[26:27]
	s_add_u32 s26, s22, 0xa0000
	s_addc_u32 s27, s23, 0
	global_load_dword v44, v65, s[26:27]
	s_add_u32 s26, s22, 0x220000
	s_addc_u32 s27, s23, 0
	global_load_dword v45, v65, s[26:27]
	s_add_u32 s26, s22, 0x3a0000
	s_addc_u32 s27, s23, 0
	global_load_dword v46, v65, s[26:27]
	s_waitcnt vmcnt(21)
; __device__ __forceinline__ float bf_lo(unsigned w) { return __uint_as_float(w << 16); }
; __device__ __forceinline__ float bf_hi(unsigned w) { return __uint_as_float(w & 0xffff0000u); }
; __device__ __forceinline__ unsigned pk2(float lo, float hi) { return pg8::cvt_pk_bf16(lo, hi); }
; __device__ __forceinline__ void merge_rows(const Args& a, int gw, int NGW, int lane) {
;     ...
;         for (int r = 0; r < 4; ++r) { const int m = mb + r * NGW; if (m < MT) {
;             const float mxl = fmaxf(l[r][0], fmaxf(l[r][1], l[r][2]));
;             float a0 = __expf(l[r][0] - mxl), a1 = __expf(l[r][1] - mxl), a2 = __expf(l[r][2] - mxl); const float is = 1.0f / (a0 + a1 + a2); a0 *= is; a1 *= is; a2 *= is;
;             const v2u o0 = o[r][0], o1 = o[r][1], o2 = o[r][2];
;             v2u w;
;             w.x = pk2(a0 * pg8::bf_lo(o0.x) + a1 * pg8::bf_lo(o1.x) + a2 * pg8::bf_lo(o2.x), a0 * pg8::bf_hi(o0.x) + a1 * pg8::bf_hi(o1.x) + a2 * pg8::bf_hi(o2.x));
;             w.y = pk2(a0 * pg8::bf_lo(o0.y) + a1 * pg8::bf_lo(o1.y) + a2 * pg8::bf_lo(o2.y), a0 * pg8::bf_hi(o0.y) + a1 * pg8::bf_hi(o1.y) + a2 * pg8::bf_hi(o2.y));
;             *(v2u*)(YAT + (size_t)m * 256 + 4 * lane) = w; } }
	v_max3_f32 v68, v60, v61, v62
	v_sub_f32_e32 v69, v60, v68
	v_sub_f32_e32 v70, v61, v68
	v_sub_f32_e32 v71, v62, v68
	v_mul_f32_e32 v69, 0x3fb8aa3b, v69
	v_mul_f32_e32 v70, 0x3fb8aa3b, v70
	v_mul_f32_e32 v71, 0x3fb8aa3b, v71
	v_exp_f32_e32 v69, v69
	v_exp_f32_e32 v70, v70
	v_exp_f32_e32 v71, v71
	s_nop 0
	v_add_f32_e32 v72, v69, v70
	v_add_f32_e32 v72, v71, v72
	v_div_scale_f32 v73, s[28:29], v72, v72, 1.0
	v_rcp_f32_e32 v74, v73
	v_div_scale_f32 v75, vcc, 1.0, v72, 1.0
	s_nop 0
	v_fma_f32 v76, -v73, v74, 1.0
	v_fmac_f32_e32 v74, v76, v74
	v_mul_f32_e32 v77, v75, v74
	v_fma_f32 v76, -v73, v77, v75
	v_fmac_f32_e32 v77, v76, v74
	v_fma_f32 v73, -v73, v77, v75
	v_div_fmas_f32 v73, v73, v74, v77
	v_div_fixup_f32 v72, v73, v72, 1.0
	v_mul_f32_e32 v69, v69, v72
	v_mul_f32_e32 v70, v70, v72
	v_mul_f32_e32 v71, v71, v72
	v_lshlrev_b32_e32 v78, 16, v48
	v_and_b32_e32 v81, 0xffff0000, v48
	v_lshlrev_b32_e32 v79, 16, v52
	v_and_b32_e32 v82, 0xffff0000, v52
	v_lshlrev_b32_e32 v80, 16, v56
	v_and_b32_e32 v83, 0xffff0000, v56
	v_mul_f32_e32 v84, v69, v78
	v_mul_f32_e32 v85, v69, v81
	v_fmac_f32_e32 v84, v70, v79
	v_fmac_f32_e32 v85, v70, v82
	v_fmac_f32_e32 v84, v71, v80
	v_fmac_f32_e32 v85, v71, v83
	v_cvt_pk_bf16_f32 v100, v84, v85
	v_lshlrev_b32_e32 v78, 16, v49
	v_and_b32_e32 v81, 0xffff0000, v49
	v_lshlrev_b32_e32 v79, 16, v53
	v_and_b32_e32 v82, 0xffff0000, v53
	v_lshlrev_b32_e32 v80, 16, v57
	v_and_b32_e32 v83, 0xffff0000, v57
	v_mul_f32_e32 v84, v69, v78
	v_mul_f32_e32 v85, v69, v81
	v_fmac_f32_e32 v84, v70, v79
	v_fmac_f32_e32 v85, v70, v82
	v_fmac_f32_e32 v84, v71, v80
	v_fmac_f32_e32 v85, v71, v83
	v_cvt_pk_bf16_f32 v101, v84, v85
	v_lshlrev_b32_e32 v78, 16, v50
	v_and_b32_e32 v81, 0xffff0000, v50
	v_lshlrev_b32_e32 v79, 16, v54
	v_and_b32_e32 v82, 0xffff0000, v54
	v_lshlrev_b32_e32 v80, 16, v58
	v_and_b32_e32 v83, 0xffff0000, v58
	v_mul_f32_e32 v84, v69, v78
	v_mul_f32_e32 v85, v69, v81
	v_fmac_f32_e32 v84, v70, v79
	v_fmac_f32_e32 v85, v70, v82
	v_fmac_f32_e32 v84, v71, v80
	v_fmac_f32_e32 v85, v71, v83
	v_cvt_pk_bf16_f32 v102, v84, v85
	v_lshlrev_b32_e32 v78, 16, v51
	v_and_b32_e32 v81, 0xffff0000, v51
	v_lshlrev_b32_e32 v79, 16, v55
	v_and_b32_e32 v82, 0xffff0000, v55
	v_lshlrev_b32_e32 v80, 16, v59
	v_and_b32_e32 v83, 0xffff0000, v59
	v_mul_f32_e32 v84, v69, v78
	v_mul_f32_e32 v85, v69, v81
	v_fmac_f32_e32 v84, v70, v79
	v_fmac_f32_e32 v85, v70, v82
	v_fmac_f32_e32 v84, v71, v80
	v_fmac_f32_e32 v85, v71, v83
	v_cvt_pk_bf16_f32 v103, v84, v85
	s_add_u32 s26, s24, 0xe00000
	s_addc_u32 s27, s25, 0
	global_store_dwordx4 v64, v[100:103], s[26:27]
	s_add_u32 s26, s20, 0x1600000
	s_addc_u32 s27, s21, 0
	global_load_dwordx4 v[48:51], v64, s[26:27]
	s_add_u32 s26, s20, 0x4600000
	s_addc_u32 s27, s21, 0
	global_load_dwordx4 v[52:55], v64, s[26:27]
	s_add_u32 s26, s20, 0x7600000
	s_addc_u32 s27, s21, 0
	global_load_dwordx4 v[56:59], v64, s[26:27]
	s_add_u32 s26, s22, 0xb0000
	s_addc_u32 s27, s23, 0
	global_load_dword v60, v65, s[26:27]
	s_add_u32 s26, s22, 0x230000
	s_addc_u32 s27, s23, 0
	global_load_dword v61, v65, s[26:27]
	s_add_u32 s26, s22, 0x3b0000
	s_addc_u32 s27, s23, 0
	global_load_dword v62, v65, s[26:27]
	s_waitcnt vmcnt(21)
	v_max3_f32 v68, v12, v13, v14
	v_sub_f32_e32 v69, v12, v68
	v_sub_f32_e32 v70, v13, v68
	v_sub_f32_e32 v71, v14, v68
	v_mul_f32_e32 v69, 0x3fb8aa3b, v69
	v_mul_f32_e32 v70, 0x3fb8aa3b, v70
	v_mul_f32_e32 v71, 0x3fb8aa3b, v71
	v_exp_f32_e32 v69, v69
	v_exp_f32_e32 v70, v70
	v_exp_f32_e32 v71, v71
	s_nop 0
	v_add_f32_e32 v72, v69, v70
	v_add_f32_e32 v72, v71, v72
	v_div_scale_f32 v73, s[28:29], v72, v72, 1.0
	v_rcp_f32_e32 v74, v73
	v_div_scale_f32 v75, vcc, 1.0, v72, 1.0
	s_nop 0
	v_fma_f32 v76, -v73, v74, 1.0
	v_fmac_f32_e32 v74, v76, v74
	v_mul_f32_e32 v77, v75, v74
	v_fma_f32 v76, -v73, v77, v75
	v_fmac_f32_e32 v77, v76, v74
	v_fma_f32 v73, -v73, v77, v75
	v_div_fmas_f32 v73, v73, v74, v77
	v_div_fixup_f32 v72, v73, v72, 1.0
	v_mul_f32_e32 v69, v69, v72
	v_mul_f32_e32 v70, v70, v72
	v_mul_f32_e32 v71, v71, v72
	v_lshlrev_b32_e32 v78, 16, v0
	v_and_b32_e32 v81, 0xffff0000, v0
	v_lshlrev_b32_e32 v79, 16, v4
	v_and_b32_e32 v82, 0xffff0000, v4
	v_lshlrev_b32_e32 v80, 16, v8
	v_and_b32_e32 v83, 0xffff0000, v8
	v_mul_f32_e32 v84, v69, v78
	v_mul_f32_e32 v85, v69, v81
	v_fmac_f32_e32 v84, v70, v79
	v_fmac_f32_e32 v85, v70, v82
	v_fmac_f32_e32 v84, v71, v80
	v_fmac_f32_e32 v85, v71, v83
	v_cvt_pk_bf16_f32 v96, v84, v85
	v_lshlrev_b32_e32 v78, 16, v1
	v_and_b32_e32 v81, 0xffff0000, v1
	v_lshlrev_b32_e32 v79, 16, v5
	v_and_b32_e32 v82, 0xffff0000, v5
	v_lshlrev_b32_e32 v80, 16, v9
	v_and_b32_e32 v83, 0xffff0000, v9
	v_mul_f32_e32 v84, v69, v78
	v_mul_f32_e32 v85, v69, v81
	v_fmac_f32_e32 v84, v70, v79
	v_fmac_f32_e32 v85, v70, v82
	v_fmac_f32_e32 v84, v71, v80
	v_fmac_f32_e32 v85, v71, v83
	v_cvt_pk_bf16_f32 v97, v84, v85
	v_lshlrev_b32_e32 v78, 16, v2
	v_and_b32_e32 v81, 0xffff0000, v2
	v_lshlrev_b32_e32 v79, 16, v6
	v_and_b32_e32 v82, 0xffff0000, v6
	v_lshlrev_b32_e32 v80, 16, v10
	v_and_b32_e32 v83, 0xffff0000, v10
	v_mul_f32_e32 v84, v69, v78
	v_mul_f32_e32 v85, v69, v81
	v_fmac_f32_e32 v84, v70, v79
	v_fmac_f32_e32 v85, v70, v82
	v_fmac_f32_e32 v84, v71, v80
	v_fmac_f32_e32 v85, v71, v83
	v_cvt_pk_bf16_f32 v98, v84, v85
	v_lshlrev_b32_e32 v78, 16, v3
	v_and_b32_e32 v81, 0xffff0000, v3
	v_lshlrev_b32_e32 v79, 16, v7
	v_and_b32_e32 v82, 0xffff0000, v7
	v_lshlrev_b32_e32 v80, 16, v11
	v_and_b32_e32 v83, 0xffff0000, v11
	v_mul_f32_e32 v84, v69, v78
	v_mul_f32_e32 v85, v69, v81
	v_fmac_f32_e32 v84, v70, v79
	v_fmac_f32_e32 v85, v70, v82
	v_fmac_f32_e32 v84, v71, v80
	v_fmac_f32_e32 v85, v71, v83
	v_cvt_pk_bf16_f32 v99, v84, v85
	s_add_u32 s26, s24, 0x1000000
	s_addc_u32 s27, s25, 0
	global_store_dwordx4 v64, v[96:99], s[26:27]
	s_add_u32 s26, s20, 0x1800000
	s_addc_u32 s27, s21, 0
	global_load_dwordx4 v[0:3], v64, s[26:27]
	s_add_u32 s26, s20, 0x4800000
	s_addc_u32 s27, s21, 0
	global_load_dwordx4 v[4:7], v64, s[26:27]
	s_add_u32 s26, s20, 0x7800000
	s_addc_u32 s27, s21, 0
	global_load_dwordx4 v[8:11], v64, s[26:27]
	s_add_u32 s26, s22, 0xc0000
	s_addc_u32 s27, s23, 0
	global_load_dword v12, v65, s[26:27]
	s_add_u32 s26, s22, 0x240000
	s_addc_u32 s27, s23, 0
	global_load_dword v13, v65, s[26:27]
	s_add_u32 s26, s22, 0x3c0000
	s_addc_u32 s27, s23, 0
	global_load_dword v14, v65, s[26:27]
	s_waitcnt vmcnt(21)
; __device__ __forceinline__ float bf_lo(unsigned w) { return __uint_as_float(w << 16); }
; __device__ __forceinline__ float bf_hi(unsigned w) { return __uint_as_float(w & 0xffff0000u); }
; __device__ __forceinline__ unsigned pk2(float lo, float hi) { return pg8::cvt_pk_bf16(lo, hi); }
; __device__ __forceinline__ void merge_rows(const Args& a, int gw, int NGW, int lane) {
;     ...
;         for (int r = 0; r < 4; ++r) { const int m = mb + r * NGW; if (m < MT) {
;             const float mxl = fmaxf(l[r][0], fmaxf(l[r][1], l[r][2]));
;             float a0 = __expf(l[r][0] - mxl), a1 = __expf(l[r][1] - mxl), a2 = __expf(l[r][2] - mxl); const float is = 1.0f / (a0 + a1 + a2); a0 *= is; a1 *= is; a2 *= is;
;             const v2u o0 = o[r][0], o1 = o[r][1], o2 = o[r][2];
;             v2u w;
;             w.x = pk2(a0 * pg8::bf_lo(o0.x) + a1 * pg8::bf_lo(o1.x) + a2 * pg8::bf_lo(o2.x), a0 * pg8::bf_hi(o0.x) + a1 * pg8::bf_hi(o1.x) + a2 * pg8::bf_hi(o2.x));
;             w.y = pk2(a0 * pg8::bf_lo(o0.y) + a1 * pg8::bf_lo(o1.y) + a2 * pg8::bf_lo(o2.y), a0 * pg8::bf_hi(o0.y) + a1 * pg8::bf_hi(o1.y) + a2 * pg8::bf_hi(o2.y));
;             *(v2u*)(YAT + (size_t)m * 256 + 4 * lane) = w; } }
	v_max3_f32 v68, v28, v29, v30
	v_sub_f32_e32 v69, v28, v68
	v_sub_f32_e32 v70, v29, v68
	v_sub_f32_e32 v71, v30, v68
	v_mul_f32_e32 v69, 0x3fb8aa3b, v69
	v_mul_f32_e32 v70, 0x3fb8aa3b, v70
	v_mul_f32_e32 v71, 0x3fb8aa3b, v71
	v_exp_f32_e32 v69, v69
	v_exp_f32_e32 v70, v70
	v_exp_f32_e32 v71, v71
	s_nop 0
	v_add_f32_e32 v72, v69, v70
	v_add_f32_e32 v72, v71, v72
	v_div_scale_f32 v73, s[28:29], v72, v72, 1.0
	v_rcp_f32_e32 v74, v73
	v_div_scale_f32 v75, vcc, 1.0, v72, 1.0
	s_nop 0
	v_fma_f32 v76, -v73, v74, 1.0
	v_fmac_f32_e32 v74, v76, v74
	v_mul_f32_e32 v77, v75, v74
	v_fma_f32 v76, -v73, v77, v75
	v_fmac_f32_e32 v77, v76, v74
	v_fma_f32 v73, -v73, v77, v75
	v_div_fmas_f32 v73, v73, v74, v77
	v_div_fixup_f32 v72, v73, v72, 1.0
	v_mul_f32_e32 v69, v69, v72
	v_mul_f32_e32 v70, v70, v72
	v_mul_f32_e32 v71, v71, v72
	v_lshlrev_b32_e32 v78, 16, v16
	v_and_b32_e32 v81, 0xffff0000, v16
	v_lshlrev_b32_e32 v79, 16, v20
	v_and_b32_e32 v82, 0xffff0000, v20
	v_lshlrev_b32_e32 v80, 16, v24
	v_and_b32_e32 v83, 0xffff0000, v24
	v_mul_f32_e32 v84, v69, v78
	v_mul_f32_e32 v85, v69, v81
	v_fmac_f32_e32 v84, v70, v79
	v_fmac_f32_e32 v85, v70, v82
	v_fmac_f32_e32 v84, v71, v80
	v_fmac_f32_e32 v85, v71, v83
	v_cvt_pk_bf16_f32 v100, v84, v85
	v_lshlrev_b32_e32 v78, 16, v17
	v_and_b32_e32 v81, 0xffff0000, v17
	v_lshlrev_b32_e32 v79, 16, v21
	v_and_b32_e32 v82, 0xffff0000, v21
	v_lshlrev_b32_e32 v80, 16, v25
	v_and_b32_e32 v83, 0xffff0000, v25
	v_mul_f32_e32 v84, v69, v78
	v_mul_f32_e32 v85, v69, v81
	v_fmac_f32_e32 v84, v70, v79
	v_fmac_f32_e32 v85, v70, v82
	v_fmac_f32_e32 v84, v71, v80
	v_fmac_f32_e32 v85, v71, v83
	v_cvt_pk_bf16_f32 v101, v84, v85
	v_lshlrev_b32_e32 v78, 16, v18
	v_and_b32_e32 v81, 0xffff0000, v18
	v_lshlrev_b32_e32 v79, 16, v22
	v_and_b32_e32 v82, 0xffff0000, v22
	v_lshlrev_b32_e32 v80, 16, v26
	v_and_b32_e32 v83, 0xffff0000, v26
	v_mul_f32_e32 v84, v69, v78
	v_mul_f32_e32 v85, v69, v81
	v_fmac_f32_e32 v84, v70, v79
	v_fmac_f32_e32 v85, v70, v82
	v_fmac_f32_e32 v84, v71, v80
	v_fmac_f32_e32 v85, v71, v83
	v_cvt_pk_bf16_f32 v102, v84, v85
	v_lshlrev_b32_e32 v78, 16, v19
	v_and_b32_e32 v81, 0xffff0000, v19
	v_lshlrev_b32_e32 v79, 16, v23
	v_and_b32_e32 v82, 0xffff0000, v23
	v_lshlrev_b32_e32 v80, 16, v27
	v_and_b32_e32 v83, 0xffff0000, v27
	v_mul_f32_e32 v84, v69, v78
	v_mul_f32_e32 v85, v69, v81
	v_fmac_f32_e32 v84, v70, v79
	v_fmac_f32_e32 v85, v70, v82
	v_fmac_f32_e32 v84, v71, v80
	v_fmac_f32_e32 v85, v71, v83
	v_cvt_pk_bf16_f32 v103, v84, v85
	s_add_u32 s26, s24, 0x1200000
	s_addc_u32 s27, s25, 0
	global_store_dwordx4 v64, v[100:103], s[26:27]
	s_add_u32 s26, s20, 0x1a00000
	s_addc_u32 s27, s21, 0
	global_load_dwordx4 v[16:19], v64, s[26:27]
	s_add_u32 s26, s20, 0x4a00000
	s_addc_u32 s27, s21, 0
	global_load_dwordx4 v[20:23], v64, s[26:27]
	s_add_u32 s26, s20, 0x7a00000
	s_addc_u32 s27, s21, 0
	global_load_dwordx4 v[24:27], v64, s[26:27]
	s_add_u32 s26, s22, 0xd0000
	s_addc_u32 s27, s23, 0
	global_load_dword v28, v65, s[26:27]
	s_add_u32 s26, s22, 0x250000
	s_addc_u32 s27, s23, 0
	global_load_dword v29, v65, s[26:27]
	s_add_u32 s26, s22, 0x3d0000
	s_addc_u32 s27, s23, 0
	global_load_dword v30, v65, s[26:27]
	s_waitcnt vmcnt(21)
	v_max3_f32 v68, v44, v45, v46
	v_sub_f32_e32 v69, v44, v68
	v_sub_f32_e32 v70, v45, v68
	v_sub_f32_e32 v71, v46, v68
	v_mul_f32_e32 v69, 0x3fb8aa3b, v69
	v_mul_f32_e32 v70, 0x3fb8aa3b, v70
	v_mul_f32_e32 v71, 0x3fb8aa3b, v71
	v_exp_f32_e32 v69, v69
	v_exp_f32_e32 v70, v70
	v_exp_f32_e32 v71, v71
	s_nop 0
	v_add_f32_e32 v72, v69, v70
	v_add_f32_e32 v72, v71, v72
	v_div_scale_f32 v73, s[28:29], v72, v72, 1.0
	v_rcp_f32_e32 v74, v73
	v_div_scale_f32 v75, vcc, 1.0, v72, 1.0
	s_nop 0
	v_fma_f32 v76, -v73, v74, 1.0
	v_fmac_f32_e32 v74, v76, v74
	v_mul_f32_e32 v77, v75, v74
	v_fma_f32 v76, -v73, v77, v75
	v_fmac_f32_e32 v77, v76, v74
	v_fma_f32 v73, -v73, v77, v75
	v_div_fmas_f32 v73, v73, v74, v77
	v_div_fixup_f32 v72, v73, v72, 1.0
	v_mul_f32_e32 v69, v69, v72
	v_mul_f32_e32 v70, v70, v72
	v_mul_f32_e32 v71, v71, v72
	v_lshlrev_b32_e32 v78, 16, v32
	v_and_b32_e32 v81, 0xffff0000, v32
	v_lshlrev_b32_e32 v79, 16, v36
	v_and_b32_e32 v82, 0xffff0000, v36
	v_lshlrev_b32_e32 v80, 16, v40
	v_and_b32_e32 v83, 0xffff0000, v40
	v_mul_f32_e32 v84, v69, v78
	v_mul_f32_e32 v85, v69, v81
	v_fmac_f32_e32 v84, v70, v79
	v_fmac_f32_e32 v85, v70, v82
	v_fmac_f32_e32 v84, v71, v80
	v_fmac_f32_e32 v85, v71, v83
	v_cvt_pk_bf16_f32 v96, v84, v85
	v_lshlrev_b32_e32 v78, 16, v33
	v_and_b32_e32 v81, 0xffff0000, v33
	v_lshlrev_b32_e32 v79, 16, v37
	v_and_b32_e32 v82, 0xffff0000, v37
	v_lshlrev_b32_e32 v80, 16, v41
	v_and_b32_e32 v83, 0xffff0000, v41
	v_mul_f32_e32 v84, v69, v78
	v_mul_f32_e32 v85, v69, v81
	v_fmac_f32_e32 v84, v70, v79
	v_fmac_f32_e32 v85, v70, v82
	v_fmac_f32_e32 v84, v71, v80
	v_fmac_f32_e32 v85, v71, v83
	v_cvt_pk_bf16_f32 v97, v84, v85
	v_lshlrev_b32_e32 v78, 16, v34
	v_and_b32_e32 v81, 0xffff0000, v34
	v_lshlrev_b32_e32 v79, 16, v38
	v_and_b32_e32 v82, 0xffff0000, v38
	v_lshlrev_b32_e32 v80, 16, v42
	v_and_b32_e32 v83, 0xffff0000, v42
	v_mul_f32_e32 v84, v69, v78
	v_mul_f32_e32 v85, v69, v81
	v_fmac_f32_e32 v84, v70, v79
	v_fmac_f32_e32 v85, v70, v82
	v_fmac_f32_e32 v84, v71, v80
	v_fmac_f32_e32 v85, v71, v83
	v_cvt_pk_bf16_f32 v98, v84, v85
	v_lshlrev_b32_e32 v78, 16, v35
	v_and_b32_e32 v81, 0xffff0000, v35
	v_lshlrev_b32_e32 v79, 16, v39
	v_and_b32_e32 v82, 0xffff0000, v39
	v_lshlrev_b32_e32 v80, 16, v43
	v_and_b32_e32 v83, 0xffff0000, v43
	v_mul_f32_e32 v84, v69, v78
	v_mul_f32_e32 v85, v69, v81
	v_fmac_f32_e32 v84, v70, v79
	v_fmac_f32_e32 v85, v70, v82
	v_fmac_f32_e32 v84, v71, v80
	v_fmac_f32_e32 v85, v71, v83
	v_cvt_pk_bf16_f32 v99, v84, v85
	s_add_u32 s26, s24, 0x1400000
	s_addc_u32 s27, s25, 0
	global_store_dwordx4 v64, v[96:99], s[26:27]
	s_add_u32 s26, s20, 0x1c00000
	s_addc_u32 s27, s21, 0
	global_load_dwordx4 v[32:35], v64, s[26:27]
	s_add_u32 s26, s20, 0x4c00000
	s_addc_u32 s27, s21, 0
	global_load_dwordx4 v[36:39], v64, s[26:27]
	s_add_u32 s26, s20, 0x7c00000
	s_addc_u32 s27, s21, 0
	global_load_dwordx4 v[40:43], v64, s[26:27]
	s_add_u32 s26, s22, 0xe0000
	s_addc_u32 s27, s23, 0
	global_load_dword v44, v65, s[26:27]
	s_add_u32 s26, s22, 0x260000
	s_addc_u32 s27, s23, 0
	global_load_dword v45, v65, s[26:27]
	s_add_u32 s26, s22, 0x3e0000
	s_addc_u32 s27, s23, 0
	global_load_dword v46, v65, s[26:27]
	s_waitcnt vmcnt(21)
; __device__ __forceinline__ float bf_lo(unsigned w) { return __uint_as_float(w << 16); }
; __device__ __forceinline__ float bf_hi(unsigned w) { return __uint_as_float(w & 0xffff0000u); }
; __device__ __forceinline__ unsigned pk2(float lo, float hi) { return pg8::cvt_pk_bf16(lo, hi); }
; __device__ __forceinline__ void merge_rows(const Args& a, int gw, int NGW, int lane) {
;     ...
;         for (int r = 0; r < 4; ++r) { const int m = mb + r * NGW; if (m < MT) {
;             const float mxl = fmaxf(l[r][0], fmaxf(l[r][1], l[r][2]));
;             float a0 = __expf(l[r][0] - mxl), a1 = __expf(l[r][1] - mxl), a2 = __expf(l[r][2] - mxl); const float is = 1.0f / (a0 + a1 + a2); a0 *= is; a1 *= is; a2 *= is;
;             const v2u o0 = o[r][0], o1 = o[r][1], o2 = o[r][2];
;             v2u w;
;             w.x = pk2(a0 * pg8::bf_lo(o0.x) + a1 * pg8::bf_lo(o1.x) + a2 * pg8::bf_lo(o2.x), a0 * pg8::bf_hi(o0.x) + a1 * pg8::bf_hi(o1.x) + a2 * pg8::bf_hi(o2.x));
;             w.y = pk2(a0 * pg8::bf_lo(o0.y) + a1 * pg8::bf_lo(o1.y) + a2 * pg8::bf_lo(o2.y), a0 * pg8::bf_hi(o0.y) + a1 * pg8::bf_hi(o1.y) + a2 * pg8::bf_hi(o2.y));
;             *(v2u*)(YAT + (size_t)m * 256 + 4 * lane) = w; } }
	v_max3_f32 v68, v60, v61, v62
	v_sub_f32_e32 v69, v60, v68
	v_sub_f32_e32 v70, v61, v68
	v_sub_f32_e32 v71, v62, v68
	v_mul_f32_e32 v69, 0x3fb8aa3b, v69
	v_mul_f32_e32 v70, 0x3fb8aa3b, v70
	v_mul_f32_e32 v71, 0x3fb8aa3b, v71
	v_exp_f32_e32 v69, v69
	v_exp_f32_e32 v70, v70
	v_exp_f32_e32 v71, v71
	s_nop 0
	v_add_f32_e32 v72, v69, v70
	v_add_f32_e32 v72, v71, v72
	v_div_scale_f32 v73, s[28:29], v72, v72, 1.0
	v_rcp_f32_e32 v74, v73
	v_div_scale_f32 v75, vcc, 1.0, v72, 1.0
	s_nop 0
	v_fma_f32 v76, -v73, v74, 1.0
	v_fmac_f32_e32 v74, v76, v74
	v_mul_f32_e32 v77, v75, v74
	v_fma_f32 v76, -v73, v77, v75
	v_fmac_f32_e32 v77, v76, v74
	v_fma_f32 v73, -v73, v77, v75
	v_div_fmas_f32 v73, v73, v74, v77
	v_div_fixup_f32 v72, v73, v72, 1.0
	v_mul_f32_e32 v69, v69, v72
	v_mul_f32_e32 v70, v70, v72
	v_mul_f32_e32 v71, v71, v72
	v_lshlrev_b32_e32 v78, 16, v48
	v_and_b32_e32 v81, 0xffff0000, v48
	v_lshlrev_b32_e32 v79, 16, v52
	v_and_b32_e32 v82, 0xffff0000, v52
	v_lshlrev_b32_e32 v80, 16, v56
	v_and_b32_e32 v83, 0xffff0000, v56
	v_mul_f32_e32 v84, v69, v78
	v_mul_f32_e32 v85, v69, v81
	v_fmac_f32_e32 v84, v70, v79
	v_fmac_f32_e32 v85, v70, v82
	v_fmac_f32_e32 v84, v71, v80
	v_fmac_f32_e32 v85, v71, v83
	v_cvt_pk_bf16_f32 v100, v84, v85
	v_lshlrev_b32_e32 v78, 16, v49
	v_and_b32_e32 v81, 0xffff0000, v49
	v_lshlrev_b32_e32 v79, 16, v53
	v_and_b32_e32 v82, 0xffff0000, v53
	v_lshlrev_b32_e32 v80, 16, v57
	v_and_b32_e32 v83, 0xffff0000, v57
	v_mul_f32_e32 v84, v69, v78
	v_mul_f32_e32 v85, v69, v81
	v_fmac_f32_e32 v84, v70, v79
	v_fmac_f32_e32 v85, v70, v82
	v_fmac_f32_e32 v84, v71, v80
	v_fmac_f32_e32 v85, v71, v83
	v_cvt_pk_bf16_f32 v101, v84, v85
	v_lshlrev_b32_e32 v78, 16, v50
	v_and_b32_e32 v81, 0xffff0000, v50
	v_lshlrev_b32_e32 v79, 16, v54
	v_and_b32_e32 v82, 0xffff0000, v54
	v_lshlrev_b32_e32 v80, 16, v58
	v_and_b32_e32 v83, 0xffff0000, v58
	v_mul_f32_e32 v84, v69, v78
	v_mul_f32_e32 v85, v69, v81
	v_fmac_f32_e32 v84, v70, v79
	v_fmac_f32_e32 v85, v70, v82
	v_fmac_f32_e32 v84, v71, v80
	v_fmac_f32_e32 v85, v71, v83
	v_cvt_pk_bf16_f32 v102, v84, v85
	v_lshlrev_b32_e32 v78, 16, v51
	v_and_b32_e32 v81, 0xffff0000, v51
	v_lshlrev_b32_e32 v79, 16, v55
	v_and_b32_e32 v82, 0xffff0000, v55
	v_lshlrev_b32_e32 v80, 16, v59
	v_and_b32_e32 v83, 0xffff0000, v59
	v_mul_f32_e32 v84, v69, v78
	v_mul_f32_e32 v85, v69, v81
	v_fmac_f32_e32 v84, v70, v79
	v_fmac_f32_e32 v85, v70, v82
	v_fmac_f32_e32 v84, v71, v80
	v_fmac_f32_e32 v85, v71, v83
	v_cvt_pk_bf16_f32 v103, v84, v85
	s_add_u32 s26, s24, 0x1600000
	s_addc_u32 s27, s25, 0
	global_store_dwordx4 v64, v[100:103], s[26:27]
	s_add_u32 s26, s20, 0x1e00000
	s_addc_u32 s27, s21, 0
	global_load_dwordx4 v[48:51], v64, s[26:27]
	s_add_u32 s26, s20, 0x4e00000
	s_addc_u32 s27, s21, 0
	global_load_dwordx4 v[52:55], v64, s[26:27]
	s_add_u32 s26, s20, 0x7e00000
	s_addc_u32 s27, s21, 0
	global_load_dwordx4 v[56:59], v64, s[26:27]
	s_add_u32 s26, s22, 0xf0000
	s_addc_u32 s27, s23, 0
	global_load_dword v60, v65, s[26:27]
	s_add_u32 s26, s22, 0x270000
	s_addc_u32 s27, s23, 0
	global_load_dword v61, v65, s[26:27]
	s_add_u32 s26, s22, 0x3f0000
	s_addc_u32 s27, s23, 0
	global_load_dword v62, v65, s[26:27]
	s_waitcnt vmcnt(21)
	v_max3_f32 v68, v12, v13, v14
	v_sub_f32_e32 v69, v12, v68
	v_sub_f32_e32 v70, v13, v68
	v_sub_f32_e32 v71, v14, v68
	v_mul_f32_e32 v69, 0x3fb8aa3b, v69
	v_mul_f32_e32 v70, 0x3fb8aa3b, v70
	v_mul_f32_e32 v71, 0x3fb8aa3b, v71
	v_exp_f32_e32 v69, v69
	v_exp_f32_e32 v70, v70
	v_exp_f32_e32 v71, v71
	s_nop 0
	v_add_f32_e32 v72, v69, v70
	v_add_f32_e32 v72, v71, v72
	v_div_scale_f32 v73, s[28:29], v72, v72, 1.0
	v_rcp_f32_e32 v74, v73
	v_div_scale_f32 v75, vcc, 1.0, v72, 1.0
	s_nop 0
	v_fma_f32 v76, -v73, v74, 1.0
	v_fmac_f32_e32 v74, v76, v74
	v_mul_f32_e32 v77, v75, v74
	v_fma_f32 v76, -v73, v77, v75
	v_fmac_f32_e32 v77, v76, v74
	v_fma_f32 v73, -v73, v77, v75
	v_div_fmas_f32 v73, v73, v74, v77
	v_div_fixup_f32 v72, v73, v72, 1.0
	v_mul_f32_e32 v69, v69, v72
	v_mul_f32_e32 v70, v70, v72
	v_mul_f32_e32 v71, v71, v72
	v_lshlrev_b32_e32 v78, 16, v0
	v_and_b32_e32 v81, 0xffff0000, v0
	v_lshlrev_b32_e32 v79, 16, v4
	v_and_b32_e32 v82, 0xffff0000, v4
	v_lshlrev_b32_e32 v80, 16, v8
	v_and_b32_e32 v83, 0xffff0000, v8
	v_mul_f32_e32 v84, v69, v78
	v_mul_f32_e32 v85, v69, v81
	v_fmac_f32_e32 v84, v70, v79
	v_fmac_f32_e32 v85, v70, v82
	v_fmac_f32_e32 v84, v71, v80
	v_fmac_f32_e32 v85, v71, v83
	v_cvt_pk_bf16_f32 v96, v84, v85
	v_lshlrev_b32_e32 v78, 16, v1
	v_and_b32_e32 v81, 0xffff0000, v1
	v_lshlrev_b32_e32 v79, 16, v5
	v_and_b32_e32 v82, 0xffff0000, v5
	v_lshlrev_b32_e32 v80, 16, v9
	v_and_b32_e32 v83, 0xffff0000, v9
	v_mul_f32_e32 v84, v69, v78
	v_mul_f32_e32 v85, v69, v81
	v_fmac_f32_e32 v84, v70, v79
	v_fmac_f32_e32 v85, v70, v82
	v_fmac_f32_e32 v84, v71, v80
	v_fmac_f32_e32 v85, v71, v83
	v_cvt_pk_bf16_f32 v97, v84, v85
	v_lshlrev_b32_e32 v78, 16, v2
	v_and_b32_e32 v81, 0xffff0000, v2
	v_lshlrev_b32_e32 v79, 16, v6
	v_and_b32_e32 v82, 0xffff0000, v6
	v_lshlrev_b32_e32 v80, 16, v10
	v_and_b32_e32 v83, 0xffff0000, v10
	v_mul_f32_e32 v84, v69, v78
	v_mul_f32_e32 v85, v69, v81
	v_fmac_f32_e32 v84, v70, v79
	v_fmac_f32_e32 v85, v70, v82
	v_fmac_f32_e32 v84, v71, v80
	v_fmac_f32_e32 v85, v71, v83
	v_cvt_pk_bf16_f32 v98, v84, v85
	v_lshlrev_b32_e32 v78, 16, v3
	v_and_b32_e32 v81, 0xffff0000, v3
	v_lshlrev_b32_e32 v79, 16, v7
	v_and_b32_e32 v82, 0xffff0000, v7
	v_lshlrev_b32_e32 v80, 16, v11
	v_and_b32_e32 v83, 0xffff0000, v11
	v_mul_f32_e32 v84, v69, v78
	v_mul_f32_e32 v85, v69, v81
	v_fmac_f32_e32 v84, v70, v79
	v_fmac_f32_e32 v85, v70, v82
	v_fmac_f32_e32 v84, v71, v80
	v_fmac_f32_e32 v85, v71, v83
	v_cvt_pk_bf16_f32 v99, v84, v85
	s_add_u32 s26, s24, 0x1800000
	s_addc_u32 s27, s25, 0
	global_store_dwordx4 v64, v[96:99], s[26:27]
	s_add_u32 s26, s20, 0x2000000
	s_addc_u32 s27, s21, 0
	global_load_dwordx4 v[0:3], v64, s[26:27]
	s_add_u32 s26, s20, 0x5000000
	s_addc_u32 s27, s21, 0
	global_load_dwordx4 v[4:7], v64, s[26:27]
	s_add_u32 s26, s20, 0x8000000
	s_addc_u32 s27, s21, 0
	global_load_dwordx4 v[8:11], v64, s[26:27]
	s_add_u32 s26, s22, 0x100000
	s_addc_u32 s27, s23, 0
	global_load_dword v12, v65, s[26:27]
	s_add_u32 s26, s22, 0x280000
	s_addc_u32 s27, s23, 0
	global_load_dword v13, v65, s[26:27]
	s_add_u32 s26, s22, 0x400000
	s_addc_u32 s27, s23, 0
	global_load_dword v14, v65, s[26:27]
	s_waitcnt vmcnt(21)
; __device__ __forceinline__ float bf_lo(unsigned w) { return __uint_as_float(w << 16); }
; __device__ __forceinline__ float bf_hi(unsigned w) { return __uint_as_float(w & 0xffff0000u); }
; __device__ __forceinline__ unsigned pk2(float lo, float hi) { return pg8::cvt_pk_bf16(lo, hi); }
; __device__ __forceinline__ void merge_rows(const Args& a, int gw, int NGW, int lane) {
;     ...
;         for (int r = 0; r < 4; ++r) { const int m = mb + r * NGW; if (m < MT) {
;             const float mxl = fmaxf(l[r][0], fmaxf(l[r][1], l[r][2]));
;             float a0 = __expf(l[r][0] - mxl), a1 = __expf(l[r][1] - mxl), a2 = __expf(l[r][2] - mxl); const float is = 1.0f / (a0 + a1 + a2); a0 *= is; a1 *= is; a2 *= is;
;             const v2u o0 = o[r][0], o1 = o[r][1], o2 = o[r][2];
;             v2u w;
;             w.x = pk2(a0 * pg8::bf_lo(o0.x) + a1 * pg8::bf_lo(o1.x) + a2 * pg8::bf_lo(o2.x), a0 * pg8::bf_hi(o0.x) + a1 * pg8::bf_hi(o1.x) + a2 * pg8::bf_hi(o2.x));
;             w.y = pk2(a0 * pg8::bf_lo(o0.y) + a1 * pg8::bf_lo(o1.y) + a2 * pg8::bf_lo(o2.y), a0 * pg8::bf_hi(o0.y) + a1 * pg8::bf_hi(o1.y) + a2 * pg8::bf_hi(o2.y));
;             *(v2u*)(YAT + (size_t)m * 256 + 4 * lane) = w; } }
	v_max3_f32 v68, v28, v29, v30
	v_sub_f32_e32 v69, v28, v68
	v_sub_f32_e32 v70, v29, v68
	v_sub_f32_e32 v71, v30, v68
	v_mul_f32_e32 v69, 0x3fb8aa3b, v69
	v_mul_f32_e32 v70, 0x3fb8aa3b, v70
	v_mul_f32_e32 v71, 0x3fb8aa3b, v71
	v_exp_f32_e32 v69, v69
	v_exp_f32_e32 v70, v70
	v_exp_f32_e32 v71, v71
	s_nop 0
	v_add_f32_e32 v72, v69, v70
	v_add_f32_e32 v72, v71, v72
	v_div_scale_f32 v73, s[28:29], v72, v72, 1.0
	v_rcp_f32_e32 v74, v73
	v_div_scale_f32 v75, vcc, 1.0, v72, 1.0
	s_nop 0
	v_fma_f32 v76, -v73, v74, 1.0
	v_fmac_f32_e32 v74, v76, v74
	v_mul_f32_e32 v77, v75, v74
	v_fma_f32 v76, -v73, v77, v75
	v_fmac_f32_e32 v77, v76, v74
	v_fma_f32 v73, -v73, v77, v75
	v_div_fmas_f32 v73, v73, v74, v77
	v_div_fixup_f32 v72, v73, v72, 1.0
	v_mul_f32_e32 v69, v69, v72
	v_mul_f32_e32 v70, v70, v72
	v_mul_f32_e32 v71, v71, v72
	v_lshlrev_b32_e32 v78, 16, v16
	v_and_b32_e32 v81, 0xffff0000, v16
	v_lshlrev_b32_e32 v79, 16, v20
	v_and_b32_e32 v82, 0xffff0000, v20
	v_lshlrev_b32_e32 v80, 16, v24
	v_and_b32_e32 v83, 0xffff0000, v24
	v_mul_f32_e32 v84, v69, v78
	v_mul_f32_e32 v85, v69, v81
	v_fmac_f32_e32 v84, v70, v79
	v_fmac_f32_e32 v85, v70, v82
	v_fmac_f32_e32 v84, v71, v80
	v_fmac_f32_e32 v85, v71, v83
	v_cvt_pk_bf16_f32 v100, v84, v85
	v_lshlrev_b32_e32 v78, 16, v17
	v_and_b32_e32 v81, 0xffff0000, v17
	v_lshlrev_b32_e32 v79, 16, v21
	v_and_b32_e32 v82, 0xffff0000, v21
	v_lshlrev_b32_e32 v80, 16, v25
	v_and_b32_e32 v83, 0xffff0000, v25
	v_mul_f32_e32 v84, v69, v78
	v_mul_f32_e32 v85, v69, v81
	v_fmac_f32_e32 v84, v70, v79
	v_fmac_f32_e32 v85, v70, v82
	v_fmac_f32_e32 v84, v71, v80
	v_fmac_f32_e32 v85, v71, v83
	v_cvt_pk_bf16_f32 v101, v84, v85
	v_lshlrev_b32_e32 v78, 16, v18
	v_and_b32_e32 v81, 0xffff0000, v18
	v_lshlrev_b32_e32 v79, 16, v22
	v_and_b32_e32 v82, 0xffff0000, v22
	v_lshlrev_b32_e32 v80, 16, v26
	v_and_b32_e32 v83, 0xffff0000, v26
	v_mul_f32_e32 v84, v69, v78
	v_mul_f32_e32 v85, v69, v81
	v_fmac_f32_e32 v84, v70, v79
	v_fmac_f32_e32 v85, v70, v82
	v_fmac_f32_e32 v84, v71, v80
	v_fmac_f32_e32 v85, v71, v83
	v_cvt_pk_bf16_f32 v102, v84, v85
	v_lshlrev_b32_e32 v78, 16, v19
	v_and_b32_e32 v81, 0xffff0000, v19
	v_lshlrev_b32_e32 v79, 16, v23
	v_and_b32_e32 v82, 0xffff0000, v23
	v_lshlrev_b32_e32 v80, 16, v27
	v_and_b32_e32 v83, 0xffff0000, v27
	v_mul_f32_e32 v84, v69, v78
	v_mul_f32_e32 v85, v69, v81
	v_fmac_f32_e32 v84, v70, v79
	v_fmac_f32_e32 v85, v70, v82
	v_fmac_f32_e32 v84, v71, v80
	v_fmac_f32_e32 v85, v71, v83
	v_cvt_pk_bf16_f32 v103, v84, v85
	s_add_u32 s26, s24, 0x1a00000
	s_addc_u32 s27, s25, 0
	global_store_dwordx4 v64, v[100:103], s[26:27]
	s_add_u32 s26, s20, 0x2200000
	s_addc_u32 s27, s21, 0
	global_load_dwordx4 v[16:19], v64, s[26:27]
	s_add_u32 s26, s20, 0x5200000
	s_addc_u32 s27, s21, 0
	global_load_dwordx4 v[20:23], v64, s[26:27]
	s_add_u32 s26, s20, 0x8200000
	s_addc_u32 s27, s21, 0
	global_load_dwordx4 v[24:27], v64, s[26:27]
	s_add_u32 s26, s22, 0x110000
	s_addc_u32 s27, s23, 0
	global_load_dword v28, v65, s[26:27]
	s_add_u32 s26, s22, 0x290000
	s_addc_u32 s27, s23, 0
	global_load_dword v29, v65, s[26:27]
	s_add_u32 s26, s22, 0x410000
	s_addc_u32 s27, s23, 0
	global_load_dword v30, v65, s[26:27]
	s_waitcnt vmcnt(21)
	v_max3_f32 v68, v44, v45, v46
	v_sub_f32_e32 v69, v44, v68
	v_sub_f32_e32 v70, v45, v68
	v_sub_f32_e32 v71, v46, v68
	v_mul_f32_e32 v69, 0x3fb8aa3b, v69
	v_mul_f32_e32 v70, 0x3fb8aa3b, v70
	v_mul_f32_e32 v71, 0x3fb8aa3b, v71
	v_exp_f32_e32 v69, v69
	v_exp_f32_e32 v70, v70
	v_exp_f32_e32 v71, v71
	s_nop 0
	v_add_f32_e32 v72, v69, v70
	v_add_f32_e32 v72, v71, v72
	v_div_scale_f32 v73, s[28:29], v72, v72, 1.0
	v_rcp_f32_e32 v74, v73
	v_div_scale_f32 v75, vcc, 1.0, v72, 1.0
	s_nop 0
	v_fma_f32 v76, -v73, v74, 1.0
	v_fmac_f32_e32 v74, v76, v74
	v_mul_f32_e32 v77, v75, v74
	v_fma_f32 v76, -v73, v77, v75
	v_fmac_f32_e32 v77, v76, v74
	v_fma_f32 v73, -v73, v77, v75
	v_div_fmas_f32 v73, v73, v74, v77
	v_div_fixup_f32 v72, v73, v72, 1.0
	v_mul_f32_e32 v69, v69, v72
	v_mul_f32_e32 v70, v70, v72
	v_mul_f32_e32 v71, v71, v72
	v_lshlrev_b32_e32 v78, 16, v32
	v_and_b32_e32 v81, 0xffff0000, v32
	v_lshlrev_b32_e32 v79, 16, v36
	v_and_b32_e32 v82, 0xffff0000, v36
	v_lshlrev_b32_e32 v80, 16, v40
	v_and_b32_e32 v83, 0xffff0000, v40
	v_mul_f32_e32 v84, v69, v78
	v_mul_f32_e32 v85, v69, v81
	v_fmac_f32_e32 v84, v70, v79
	v_fmac_f32_e32 v85, v70, v82
	v_fmac_f32_e32 v84, v71, v80
	v_fmac_f32_e32 v85, v71, v83
	v_cvt_pk_bf16_f32 v96, v84, v85
	v_lshlrev_b32_e32 v78, 16, v33
	v_and_b32_e32 v81, 0xffff0000, v33
	v_lshlrev_b32_e32 v79, 16, v37
	v_and_b32_e32 v82, 0xffff0000, v37
	v_lshlrev_b32_e32 v80, 16, v41
	v_and_b32_e32 v83, 0xffff0000, v41
	v_mul_f32_e32 v84, v69, v78
	v_mul_f32_e32 v85, v69, v81
	v_fmac_f32_e32 v84, v70, v79
	v_fmac_f32_e32 v85, v70, v82
	v_fmac_f32_e32 v84, v71, v80
	v_fmac_f32_e32 v85, v71, v83
	v_cvt_pk_bf16_f32 v97, v84, v85
	v_lshlrev_b32_e32 v78, 16, v34
	v_and_b32_e32 v81, 0xffff0000, v34
	v_lshlrev_b32_e32 v79, 16, v38
	v_and_b32_e32 v82, 0xffff0000, v38
	v_lshlrev_b32_e32 v80, 16, v42
	v_and_b32_e32 v83, 0xffff0000, v42
	v_mul_f32_e32 v84, v69, v78
	v_mul_f32_e32 v85, v69, v81
	v_fmac_f32_e32 v84, v70, v79
	v_fmac_f32_e32 v85, v70, v82
	v_fmac_f32_e32 v84, v71, v80
	v_fmac_f32_e32 v85, v71, v83
	v_cvt_pk_bf16_f32 v98, v84, v85
	v_lshlrev_b32_e32 v78, 16, v35
	v_and_b32_e32 v81, 0xffff0000, v35
	v_lshlrev_b32_e32 v79, 16, v39
	v_and_b32_e32 v82, 0xffff0000, v39
	v_lshlrev_b32_e32 v80, 16, v43
	v_and_b32_e32 v83, 0xffff0000, v43
	v_mul_f32_e32 v84, v69, v78
	v_mul_f32_e32 v85, v69, v81
	v_fmac_f32_e32 v84, v70, v79
	v_fmac_f32_e32 v85, v70, v82
	v_fmac_f32_e32 v84, v71, v80
	v_fmac_f32_e32 v85, v71, v83
	v_cvt_pk_bf16_f32 v99, v84, v85
	s_add_u32 s26, s24, 0x1c00000
	s_addc_u32 s27, s25, 0
	global_store_dwordx4 v64, v[96:99], s[26:27]
	s_add_u32 s26, s20, 0x2400000
	s_addc_u32 s27, s21, 0
	global_load_dwordx4 v[32:35], v64, s[26:27]
	s_add_u32 s26, s20, 0x5400000
	s_addc_u32 s27, s21, 0
	global_load_dwordx4 v[36:39], v64, s[26:27]
	s_add_u32 s26, s20, 0x8400000
	s_addc_u32 s27, s21, 0
	global_load_dwordx4 v[40:43], v64, s[26:27]
	s_add_u32 s26, s22, 0x120000
	s_addc_u32 s27, s23, 0
	global_load_dword v44, v65, s[26:27]
	s_add_u32 s26, s22, 0x2a0000
	s_addc_u32 s27, s23, 0
	global_load_dword v45, v65, s[26:27]
	s_add_u32 s26, s22, 0x420000
	s_addc_u32 s27, s23, 0
	global_load_dword v46, v65, s[26:27]
	s_waitcnt vmcnt(21)
; __device__ __forceinline__ float bf_lo(unsigned w) { return __uint_as_float(w << 16); }
; __device__ __forceinline__ float bf_hi(unsigned w) { return __uint_as_float(w & 0xffff0000u); }
; __device__ __forceinline__ unsigned pk2(float lo, float hi) { return pg8::cvt_pk_bf16(lo, hi); }
; __device__ __forceinline__ void merge_rows(const Args& a, int gw, int NGW, int lane) {
;     ...
;         for (int r = 0; r < 4; ++r) { const int m = mb + r * NGW; if (m < MT) {
;             const float mxl = fmaxf(l[r][0], fmaxf(l[r][1], l[r][2]));
;             float a0 = __expf(l[r][0] - mxl), a1 = __expf(l[r][1] - mxl), a2 = __expf(l[r][2] - mxl); const float is = 1.0f / (a0 + a1 + a2); a0 *= is; a1 *= is; a2 *= is;
;             const v2u o0 = o[r][0], o1 = o[r][1], o2 = o[r][2];
;             v2u w;
;             w.x = pk2(a0 * pg8::bf_lo(o0.x) + a1 * pg8::bf_lo(o1.x) + a2 * pg8::bf_lo(o2.x), a0 * pg8::bf_hi(o0.x) + a1 * pg8::bf_hi(o1.x) + a2 * pg8::bf_hi(o2.x));
;             w.y = pk2(a0 * pg8::bf_lo(o0.y) + a1 * pg8::bf_lo(o1.y) + a2 * pg8::bf_lo(o2.y), a0 * pg8::bf_hi(o0.y) + a1 * pg8::bf_hi(o1.y) + a2 * pg8::bf_hi(o2.y));
;             *(v2u*)(YAT + (size_t)m * 256 + 4 * lane) = w; } }
	v_max3_f32 v68, v60, v61, v62
	v_sub_f32_e32 v69, v60, v68
	v_sub_f32_e32 v70, v61, v68
	v_sub_f32_e32 v71, v62, v68
	v_mul_f32_e32 v69, 0x3fb8aa3b, v69
	v_mul_f32_e32 v70, 0x3fb8aa3b, v70
	v_mul_f32_e32 v71, 0x3fb8aa3b, v71
	v_exp_f32_e32 v69, v69
	v_exp_f32_e32 v70, v70
	v_exp_f32_e32 v71, v71
	s_nop 0
	v_add_f32_e32 v72, v69, v70
	v_add_f32_e32 v72, v71, v72
	v_div_scale_f32 v73, s[28:29], v72, v72, 1.0
	v_rcp_f32_e32 v74, v73
	v_div_scale_f32 v75, vcc, 1.0, v72, 1.0
	s_nop 0
	v_fma_f32 v76, -v73, v74, 1.0
	v_fmac_f32_e32 v74, v76, v74
	v_mul_f32_e32 v77, v75, v74
	v_fma_f32 v76, -v73, v77, v75
	v_fmac_f32_e32 v77, v76, v74
	v_fma_f32 v73, -v73, v77, v75
	v_div_fmas_f32 v73, v73, v74, v77
	v_div_fixup_f32 v72, v73, v72, 1.0
	v_mul_f32_e32 v69, v69, v72
	v_mul_f32_e32 v70, v70, v72
	v_mul_f32_e32 v71, v71, v72
	v_lshlrev_b32_e32 v78, 16, v48
	v_and_b32_e32 v81, 0xffff0000, v48
	v_lshlrev_b32_e32 v79, 16, v52
	v_and_b32_e32 v82, 0xffff0000, v52
	v_lshlrev_b32_e32 v80, 16, v56
	v_and_b32_e32 v83, 0xffff0000, v56
	v_mul_f32_e32 v84, v69, v78
	v_mul_f32_e32 v85, v69, v81
	v_fmac_f32_e32 v84, v70, v79
	v_fmac_f32_e32 v85, v70, v82
	v_fmac_f32_e32 v84, v71, v80
	v_fmac_f32_e32 v85, v71, v83
	v_cvt_pk_bf16_f32 v100, v84, v85
	v_lshlrev_b32_e32 v78, 16, v49
	v_and_b32_e32 v81, 0xffff0000, v49
	v_lshlrev_b32_e32 v79, 16, v53
	v_and_b32_e32 v82, 0xffff0000, v53
	v_lshlrev_b32_e32 v80, 16, v57
	v_and_b32_e32 v83, 0xffff0000, v57
	v_mul_f32_e32 v84, v69, v78
	v_mul_f32_e32 v85, v69, v81
	v_fmac_f32_e32 v84, v70, v79
	v_fmac_f32_e32 v85, v70, v82
	v_fmac_f32_e32 v84, v71, v80
	v_fmac_f32_e32 v85, v71, v83
	v_cvt_pk_bf16_f32 v101, v84, v85
	v_lshlrev_b32_e32 v78, 16, v50
	v_and_b32_e32 v81, 0xffff0000, v50
	v_lshlrev_b32_e32 v79, 16, v54
	v_and_b32_e32 v82, 0xffff0000, v54
	v_lshlrev_b32_e32 v80, 16, v58
	v_and_b32_e32 v83, 0xffff0000, v58
	v_mul_f32_e32 v84, v69, v78
	v_mul_f32_e32 v85, v69, v81
	v_fmac_f32_e32 v84, v70, v79
	v_fmac_f32_e32 v85, v70, v82
	v_fmac_f32_e32 v84, v71, v80
	v_fmac_f32_e32 v85, v71, v83
	v_cvt_pk_bf16_f32 v102, v84, v85
	v_lshlrev_b32_e32 v78, 16, v51
	v_and_b32_e32 v81, 0xffff0000, v51
	v_lshlrev_b32_e32 v79, 16, v55
	v_and_b32_e32 v82, 0xffff0000, v55
	v_lshlrev_b32_e32 v80, 16, v59
	v_and_b32_e32 v83, 0xffff0000, v59
	v_mul_f32_e32 v84, v69, v78
	v_mul_f32_e32 v85, v69, v81
	v_fmac_f32_e32 v84, v70, v79
	v_fmac_f32_e32 v85, v70, v82
	v_fmac_f32_e32 v84, v71, v80
	v_fmac_f32_e32 v85, v71, v83
	v_cvt_pk_bf16_f32 v103, v84, v85
	s_add_u32 s26, s24, 0x1e00000
	s_addc_u32 s27, s25, 0
	global_store_dwordx4 v64, v[100:103], s[26:27]
	s_add_u32 s26, s20, 0x2600000
	s_addc_u32 s27, s21, 0
	global_load_dwordx4 v[48:51], v64, s[26:27]
	s_add_u32 s26, s20, 0x5600000
	s_addc_u32 s27, s21, 0
	global_load_dwordx4 v[52:55], v64, s[26:27]
	s_add_u32 s26, s20, 0x8600000
	s_addc_u32 s27, s21, 0
	global_load_dwordx4 v[56:59], v64, s[26:27]
	s_add_u32 s26, s22, 0x130000
	s_addc_u32 s27, s23, 0
	global_load_dword v60, v65, s[26:27]
	s_add_u32 s26, s22, 0x2b0000
	s_addc_u32 s27, s23, 0
	global_load_dword v61, v65, s[26:27]
	s_add_u32 s26, s22, 0x430000
	s_addc_u32 s27, s23, 0
	global_load_dword v62, v65, s[26:27]
	s_waitcnt vmcnt(21)
	v_max3_f32 v68, v12, v13, v14
	v_sub_f32_e32 v69, v12, v68
	v_sub_f32_e32 v70, v13, v68
	v_sub_f32_e32 v71, v14, v68
	v_mul_f32_e32 v69, 0x3fb8aa3b, v69
	v_mul_f32_e32 v70, 0x3fb8aa3b, v70
	v_mul_f32_e32 v71, 0x3fb8aa3b, v71
	v_exp_f32_e32 v69, v69
	v_exp_f32_e32 v70, v70
	v_exp_f32_e32 v71, v71
	s_nop 0
	v_add_f32_e32 v72, v69, v70
	v_add_f32_e32 v72, v71, v72
	v_div_scale_f32 v73, s[28:29], v72, v72, 1.0
	v_rcp_f32_e32 v74, v73
	v_div_scale_f32 v75, vcc, 1.0, v72, 1.0
	s_nop 0
	v_fma_f32 v76, -v73, v74, 1.0
	v_fmac_f32_e32 v74, v76, v74
	v_mul_f32_e32 v77, v75, v74
	v_fma_f32 v76, -v73, v77, v75
	v_fmac_f32_e32 v77, v76, v74
	v_fma_f32 v73, -v73, v77, v75
	v_div_fmas_f32 v73, v73, v74, v77
	v_div_fixup_f32 v72, v73, v72, 1.0
	v_mul_f32_e32 v69, v69, v72
	v_mul_f32_e32 v70, v70, v72
	v_mul_f32_e32 v71, v71, v72
	v_lshlrev_b32_e32 v78, 16, v0
	v_and_b32_e32 v81, 0xffff0000, v0
	v_lshlrev_b32_e32 v79, 16, v4
	v_and_b32_e32 v82, 0xffff0000, v4
	v_lshlrev_b32_e32 v80, 16, v8
	v_and_b32_e32 v83, 0xffff0000, v8
	v_mul_f32_e32 v84, v69, v78
	v_mul_f32_e32 v85, v69, v81
	v_fmac_f32_e32 v84, v70, v79
	v_fmac_f32_e32 v85, v70, v82
	v_fmac_f32_e32 v84, v71, v80
	v_fmac_f32_e32 v85, v71, v83
	v_cvt_pk_bf16_f32 v96, v84, v85
	v_lshlrev_b32_e32 v78, 16, v1
	v_and_b32_e32 v81, 0xffff0000, v1
	v_lshlrev_b32_e32 v79, 16, v5
	v_and_b32_e32 v82, 0xffff0000, v5
	v_lshlrev_b32_e32 v80, 16, v9
	v_and_b32_e32 v83, 0xffff0000, v9
	v_mul_f32_e32 v84, v69, v78
	v_mul_f32_e32 v85, v69, v81
	v_fmac_f32_e32 v84, v70, v79
	v_fmac_f32_e32 v85, v70, v82
	v_fmac_f32_e32 v84, v71, v80
	v_fmac_f32_e32 v85, v71, v83
	v_cvt_pk_bf16_f32 v97, v84, v85
	v_lshlrev_b32_e32 v78, 16, v2
	v_and_b32_e32 v81, 0xffff0000, v2
	v_lshlrev_b32_e32 v79, 16, v6
	v_and_b32_e32 v82, 0xffff0000, v6
	v_lshlrev_b32_e32 v80, 16, v10
	v_and_b32_e32 v83, 0xffff0000, v10
	v_mul_f32_e32 v84, v69, v78
	v_mul_f32_e32 v85, v69, v81
	v_fmac_f32_e32 v84, v70, v79
	v_fmac_f32_e32 v85, v70, v82
	v_fmac_f32_e32 v84, v71, v80
	v_fmac_f32_e32 v85, v71, v83
	v_cvt_pk_bf16_f32 v98, v84, v85
	v_lshlrev_b32_e32 v78, 16, v3
	v_and_b32_e32 v81, 0xffff0000, v3
	v_lshlrev_b32_e32 v79, 16, v7
	v_and_b32_e32 v82, 0xffff0000, v7
	v_lshlrev_b32_e32 v80, 16, v11
	v_and_b32_e32 v83, 0xffff0000, v11
	v_mul_f32_e32 v84, v69, v78
	v_mul_f32_e32 v85, v69, v81
	v_fmac_f32_e32 v84, v70, v79
	v_fmac_f32_e32 v85, v70, v82
	v_fmac_f32_e32 v84, v71, v80
	v_fmac_f32_e32 v85, v71, v83
	v_cvt_pk_bf16_f32 v99, v84, v85
	s_add_u32 s26, s24, 0x2000000
	s_addc_u32 s27, s25, 0
	global_store_dwordx4 v64, v[96:99], s[26:27]
	s_add_u32 s26, s20, 0x2800000
	s_addc_u32 s27, s21, 0
	global_load_dwordx4 v[0:3], v64, s[26:27]
	s_add_u32 s26, s20, 0x5800000
	s_addc_u32 s27, s21, 0
	global_load_dwordx4 v[4:7], v64, s[26:27]
	s_add_u32 s26, s20, 0x8800000
	s_addc_u32 s27, s21, 0
	global_load_dwordx4 v[8:11], v64, s[26:27]
	s_add_u32 s26, s22, 0x140000
	s_addc_u32 s27, s23, 0
	global_load_dword v12, v65, s[26:27]
	s_add_u32 s26, s22, 0x2c0000
	s_addc_u32 s27, s23, 0
	global_load_dword v13, v65, s[26:27]
	s_add_u32 s26, s22, 0x440000
	s_addc_u32 s27, s23, 0
	global_load_dword v14, v65, s[26:27]
	s_waitcnt vmcnt(21)
; __device__ __forceinline__ float bf_lo(unsigned w) { return __uint_as_float(w << 16); }
; __device__ __forceinline__ float bf_hi(unsigned w) { return __uint_as_float(w & 0xffff0000u); }
; __device__ __forceinline__ unsigned pk2(float lo, float hi) { return pg8::cvt_pk_bf16(lo, hi); }
; __device__ __forceinline__ void merge_rows(const Args& a, int gw, int NGW, int lane) {
;     ...
;         for (int r = 0; r < 4; ++r) { const int m = mb + r * NGW; if (m < MT) {
;             const float mxl = fmaxf(l[r][0], fmaxf(l[r][1], l[r][2]));
;             float a0 = __expf(l[r][0] - mxl), a1 = __expf(l[r][1] - mxl), a2 = __expf(l[r][2] - mxl); const float is = 1.0f / (a0 + a1 + a2); a0 *= is; a1 *= is; a2 *= is;
;             const v2u o0 = o[r][0], o1 = o[r][1], o2 = o[r][2];
;             v2u w;
;             w.x = pk2(a0 * pg8::bf_lo(o0.x) + a1 * pg8::bf_lo(o1.x) + a2 * pg8::bf_lo(o2.x), a0 * pg8::bf_hi(o0.x) + a1 * pg8::bf_hi(o1.x) + a2 * pg8::bf_hi(o2.x));
;             w.y = pk2(a0 * pg8::bf_lo(o0.y) + a1 * pg8::bf_lo(o1.y) + a2 * pg8::bf_lo(o2.y), a0 * pg8::bf_hi(o0.y) + a1 * pg8::bf_hi(o1.y) + a2 * pg8::bf_hi(o2.y));
;             *(v2u*)(YAT + (size_t)m * 256 + 4 * lane) = w; } }
	v_max3_f32 v68, v28, v29, v30
	v_sub_f32_e32 v69, v28, v68
	v_sub_f32_e32 v70, v29, v68
	v_sub_f32_e32 v71, v30, v68
	v_mul_f32_e32 v69, 0x3fb8aa3b, v69
	v_mul_f32_e32 v70, 0x3fb8aa3b, v70
	v_mul_f32_e32 v71, 0x3fb8aa3b, v71
	v_exp_f32_e32 v69, v69
	v_exp_f32_e32 v70, v70
	v_exp_f32_e32 v71, v71
	s_nop 0
	v_add_f32_e32 v72, v69, v70
	v_add_f32_e32 v72, v71, v72
	v_div_scale_f32 v73, s[28:29], v72, v72, 1.0
	v_rcp_f32_e32 v74, v73
	v_div_scale_f32 v75, vcc, 1.0, v72, 1.0
	s_nop 0
	v_fma_f32 v76, -v73, v74, 1.0
	v_fmac_f32_e32 v74, v76, v74
	v_mul_f32_e32 v77, v75, v74
	v_fma_f32 v76, -v73, v77, v75
	v_fmac_f32_e32 v77, v76, v74
	v_fma_f32 v73, -v73, v77, v75
	v_div_fmas_f32 v73, v73, v74, v77
	v_div_fixup_f32 v72, v73, v72, 1.0
	v_mul_f32_e32 v69, v69, v72
	v_mul_f32_e32 v70, v70, v72
	v_mul_f32_e32 v71, v71, v72
	v_lshlrev_b32_e32 v78, 16, v16
	v_and_b32_e32 v81, 0xffff0000, v16
	v_lshlrev_b32_e32 v79, 16, v20
	v_and_b32_e32 v82, 0xffff0000, v20
	v_lshlrev_b32_e32 v80, 16, v24
	v_and_b32_e32 v83, 0xffff0000, v24
	v_mul_f32_e32 v84, v69, v78
	v_mul_f32_e32 v85, v69, v81
	v_fmac_f32_e32 v84, v70, v79
	v_fmac_f32_e32 v85, v70, v82
	v_fmac_f32_e32 v84, v71, v80
	v_fmac_f32_e32 v85, v71, v83
	v_cvt_pk_bf16_f32 v100, v84, v85
	v_lshlrev_b32_e32 v78, 16, v17
	v_and_b32_e32 v81, 0xffff0000, v17
	v_lshlrev_b32_e32 v79, 16, v21
	v_and_b32_e32 v82, 0xffff0000, v21
	v_lshlrev_b32_e32 v80, 16, v25
	v_and_b32_e32 v83, 0xffff0000, v25
	v_mul_f32_e32 v84, v69, v78
	v_mul_f32_e32 v85, v69, v81
	v_fmac_f32_e32 v84, v70, v79
	v_fmac_f32_e32 v85, v70, v82
	v_fmac_f32_e32 v84, v71, v80
	v_fmac_f32_e32 v85, v71, v83
	v_cvt_pk_bf16_f32 v101, v84, v85
	v_lshlrev_b32_e32 v78, 16, v18
	v_and_b32_e32 v81, 0xffff0000, v18
	v_lshlrev_b32_e32 v79, 16, v22
	v_and_b32_e32 v82, 0xffff0000, v22
	v_lshlrev_b32_e32 v80, 16, v26
	v_and_b32_e32 v83, 0xffff0000, v26
	v_mul_f32_e32 v84, v69, v78
	v_mul_f32_e32 v85, v69, v81
	v_fmac_f32_e32 v84, v70, v79
	v_fmac_f32_e32 v85, v70, v82
	v_fmac_f32_e32 v84, v71, v80
	v_fmac_f32_e32 v85, v71, v83
	v_cvt_pk_bf16_f32 v102, v84, v85
	v_lshlrev_b32_e32 v78, 16, v19
	v_and_b32_e32 v81, 0xffff0000, v19
	v_lshlrev_b32_e32 v79, 16, v23
	v_and_b32_e32 v82, 0xffff0000, v23
	v_lshlrev_b32_e32 v80, 16, v27
	v_and_b32_e32 v83, 0xffff0000, v27
	v_mul_f32_e32 v84, v69, v78
	v_mul_f32_e32 v85, v69, v81
	v_fmac_f32_e32 v84, v70, v79
	v_fmac_f32_e32 v85, v70, v82
	v_fmac_f32_e32 v84, v71, v80
	v_fmac_f32_e32 v85, v71, v83
	v_cvt_pk_bf16_f32 v103, v84, v85
	s_add_u32 s26, s24, 0x2200000
	s_addc_u32 s27, s25, 0
	global_store_dwordx4 v64, v[100:103], s[26:27]
	s_add_u32 s26, s20, 0x2a00000
	s_addc_u32 s27, s21, 0
	global_load_dwordx4 v[16:19], v64, s[26:27]
	s_add_u32 s26, s20, 0x5a00000
	s_addc_u32 s27, s21, 0
	global_load_dwordx4 v[20:23], v64, s[26:27]
	s_add_u32 s26, s20, 0x8a00000
	s_addc_u32 s27, s21, 0
	global_load_dwordx4 v[24:27], v64, s[26:27]
	s_add_u32 s26, s22, 0x150000
	s_addc_u32 s27, s23, 0
	global_load_dword v28, v65, s[26:27]
	s_add_u32 s26, s22, 0x2d0000
	s_addc_u32 s27, s23, 0
	global_load_dword v29, v65, s[26:27]
	s_add_u32 s26, s22, 0x450000
	s_addc_u32 s27, s23, 0
	global_load_dword v30, v65, s[26:27]
	s_waitcnt vmcnt(21)
	v_max3_f32 v68, v44, v45, v46
	v_sub_f32_e32 v69, v44, v68
	v_sub_f32_e32 v70, v45, v68
	v_sub_f32_e32 v71, v46, v68
	v_mul_f32_e32 v69, 0x3fb8aa3b, v69
	v_mul_f32_e32 v70, 0x3fb8aa3b, v70
	v_mul_f32_e32 v71, 0x3fb8aa3b, v71
	v_exp_f32_e32 v69, v69
	v_exp_f32_e32 v70, v70
	v_exp_f32_e32 v71, v71
	s_nop 0
	v_add_f32_e32 v72, v69, v70
	v_add_f32_e32 v72, v71, v72
	v_div_scale_f32 v73, s[28:29], v72, v72, 1.0
	v_rcp_f32_e32 v74, v73
	v_div_scale_f32 v75, vcc, 1.0, v72, 1.0
	s_nop 0
	v_fma_f32 v76, -v73, v74, 1.0
	v_fmac_f32_e32 v74, v76, v74
	v_mul_f32_e32 v77, v75, v74
	v_fma_f32 v76, -v73, v77, v75
	v_fmac_f32_e32 v77, v76, v74
	v_fma_f32 v73, -v73, v77, v75
	v_div_fmas_f32 v73, v73, v74, v77
	v_div_fixup_f32 v72, v73, v72, 1.0
	v_mul_f32_e32 v69, v69, v72
	v_mul_f32_e32 v70, v70, v72
	v_mul_f32_e32 v71, v71, v72
	v_lshlrev_b32_e32 v78, 16, v32
	v_and_b32_e32 v81, 0xffff0000, v32
	v_lshlrev_b32_e32 v79, 16, v36
	v_and_b32_e32 v82, 0xffff0000, v36
	v_lshlrev_b32_e32 v80, 16, v40
	v_and_b32_e32 v83, 0xffff0000, v40
	v_mul_f32_e32 v84, v69, v78
	v_mul_f32_e32 v85, v69, v81
	v_fmac_f32_e32 v84, v70, v79
	v_fmac_f32_e32 v85, v70, v82
	v_fmac_f32_e32 v84, v71, v80
	v_fmac_f32_e32 v85, v71, v83
	v_cvt_pk_bf16_f32 v96, v84, v85
	v_lshlrev_b32_e32 v78, 16, v33
	v_and_b32_e32 v81, 0xffff0000, v33
	v_lshlrev_b32_e32 v79, 16, v37
	v_and_b32_e32 v82, 0xffff0000, v37
	v_lshlrev_b32_e32 v80, 16, v41
	v_and_b32_e32 v83, 0xffff0000, v41
	v_mul_f32_e32 v84, v69, v78
	v_mul_f32_e32 v85, v69, v81
	v_fmac_f32_e32 v84, v70, v79
	v_fmac_f32_e32 v85, v70, v82
	v_fmac_f32_e32 v84, v71, v80
	v_fmac_f32_e32 v85, v71, v83
	v_cvt_pk_bf16_f32 v97, v84, v85
	v_lshlrev_b32_e32 v78, 16, v34
	v_and_b32_e32 v81, 0xffff0000, v34
	v_lshlrev_b32_e32 v79, 16, v38
	v_and_b32_e32 v82, 0xffff0000, v38
	v_lshlrev_b32_e32 v80, 16, v42
	v_and_b32_e32 v83, 0xffff0000, v42
	v_mul_f32_e32 v84, v69, v78
	v_mul_f32_e32 v85, v69, v81
	v_fmac_f32_e32 v84, v70, v79
	v_fmac_f32_e32 v85, v70, v82
	v_fmac_f32_e32 v84, v71, v80
	v_fmac_f32_e32 v85, v71, v83
	v_cvt_pk_bf16_f32 v98, v84, v85
	v_lshlrev_b32_e32 v78, 16, v35
	v_and_b32_e32 v81, 0xffff0000, v35
	v_lshlrev_b32_e32 v79, 16, v39
	v_and_b32_e32 v82, 0xffff0000, v39
	v_lshlrev_b32_e32 v80, 16, v43
	v_and_b32_e32 v83, 0xffff0000, v43
	v_mul_f32_e32 v84, v69, v78
	v_mul_f32_e32 v85, v69, v81
	v_fmac_f32_e32 v84, v70, v79
	v_fmac_f32_e32 v85, v70, v82
	v_fmac_f32_e32 v84, v71, v80
	v_fmac_f32_e32 v85, v71, v83
	v_cvt_pk_bf16_f32 v99, v84, v85
	s_add_u32 s26, s24, 0x2400000
	s_addc_u32 s27, s25, 0
	global_store_dwordx4 v64, v[96:99], s[26:27]
	s_add_u32 s26, s20, 0x2c00000
	s_addc_u32 s27, s21, 0
	global_load_dwordx4 v[32:35], v64, s[26:27]
	s_add_u32 s26, s20, 0x5c00000
	s_addc_u32 s27, s21, 0
	global_load_dwordx4 v[36:39], v64, s[26:27]
	s_add_u32 s26, s20, 0x8c00000
	s_addc_u32 s27, s21, 0
	global_load_dwordx4 v[40:43], v64, s[26:27]
	s_add_u32 s26, s22, 0x160000
	s_addc_u32 s27, s23, 0
	global_load_dword v44, v65, s[26:27]
	s_add_u32 s26, s22, 0x2e0000
	s_addc_u32 s27, s23, 0
	global_load_dword v45, v65, s[26:27]
	s_add_u32 s26, s22, 0x460000
	s_addc_u32 s27, s23, 0
	global_load_dword v46, v65, s[26:27]
	s_waitcnt vmcnt(21)
; __device__ __forceinline__ float bf_lo(unsigned w) { return __uint_as_float(w << 16); }
; __device__ __forceinline__ float bf_hi(unsigned w) { return __uint_as_float(w & 0xffff0000u); }
; __device__ __forceinline__ unsigned pk2(float lo, float hi) { return pg8::cvt_pk_bf16(lo, hi); }
; __device__ __forceinline__ void merge_rows(const Args& a, int gw, int NGW, int lane) {
;     ...
;         for (int r = 0; r < 4; ++r) { const int m = mb + r * NGW; if (m < MT) {
;             const float mxl = fmaxf(l[r][0], fmaxf(l[r][1], l[r][2]));
;             float a0 = __expf(l[r][0] - mxl), a1 = __expf(l[r][1] - mxl), a2 = __expf(l[r][2] - mxl); const float is = 1.0f / (a0 + a1 + a2); a0 *= is; a1 *= is; a2 *= is;
;             const v2u o0 = o[r][0], o1 = o[r][1], o2 = o[r][2];
;             v2u w;
;             w.x = pk2(a0 * pg8::bf_lo(o0.x) + a1 * pg8::bf_lo(o1.x) + a2 * pg8::bf_lo(o2.x), a0 * pg8::bf_hi(o0.x) + a1 * pg8::bf_hi(o1.x) + a2 * pg8::bf_hi(o2.x));
;             w.y = pk2(a0 * pg8::bf_lo(o0.y) + a1 * pg8::bf_lo(o1.y) + a2 * pg8::bf_lo(o2.y), a0 * pg8::bf_hi(o0.y) + a1 * pg8::bf_hi(o1.y) + a2 * pg8::bf_hi(o2.y));
;             *(v2u*)(YAT + (size_t)m * 256 + 4 * lane) = w; } }
	v_max3_f32 v68, v60, v61, v62
	v_sub_f32_e32 v69, v60, v68
	v_sub_f32_e32 v70, v61, v68
	v_sub_f32_e32 v71, v62, v68
	v_mul_f32_e32 v69, 0x3fb8aa3b, v69
	v_mul_f32_e32 v70, 0x3fb8aa3b, v70
	v_mul_f32_e32 v71, 0x3fb8aa3b, v71
	v_exp_f32_e32 v69, v69
	v_exp_f32_e32 v70, v70
	v_exp_f32_e32 v71, v71
	s_nop 0
	v_add_f32_e32 v72, v69, v70
	v_add_f32_e32 v72, v71, v72
	v_div_scale_f32 v73, s[28:29], v72, v72, 1.0
	v_rcp_f32_e32 v74, v73
	v_div_scale_f32 v75, vcc, 1.0, v72, 1.0
	s_nop 0
	v_fma_f32 v76, -v73, v74, 1.0
	v_fmac_f32_e32 v74, v76, v74
	v_mul_f32_e32 v77, v75, v74
	v_fma_f32 v76, -v73, v77, v75
	v_fmac_f32_e32 v77, v76, v74
	v_fma_f32 v73, -v73, v77, v75
	v_div_fmas_f32 v73, v73, v74, v77
	v_div_fixup_f32 v72, v73, v72, 1.0
	v_mul_f32_e32 v69, v69, v72
	v_mul_f32_e32 v70, v70, v72
	v_mul_f32_e32 v71, v71, v72
	v_lshlrev_b32_e32 v78, 16, v48
	v_and_b32_e32 v81, 0xffff0000, v48
	v_lshlrev_b32_e32 v79, 16, v52
	v_and_b32_e32 v82, 0xffff0000, v52
	v_lshlrev_b32_e32 v80, 16, v56
	v_and_b32_e32 v83, 0xffff0000, v56
	v_mul_f32_e32 v84, v69, v78
	v_mul_f32_e32 v85, v69, v81
	v_fmac_f32_e32 v84, v70, v79
	v_fmac_f32_e32 v85, v70, v82
	v_fmac_f32_e32 v84, v71, v80
	v_fmac_f32_e32 v85, v71, v83
	v_cvt_pk_bf16_f32 v100, v84, v85
	v_lshlrev_b32_e32 v78, 16, v49
	v_and_b32_e32 v81, 0xffff0000, v49
	v_lshlrev_b32_e32 v79, 16, v53
	v_and_b32_e32 v82, 0xffff0000, v53
	v_lshlrev_b32_e32 v80, 16, v57
	v_and_b32_e32 v83, 0xffff0000, v57
	v_mul_f32_e32 v84, v69, v78
	v_mul_f32_e32 v85, v69, v81
	v_fmac_f32_e32 v84, v70, v79
	v_fmac_f32_e32 v85, v70, v82
	v_fmac_f32_e32 v84, v71, v80
	v_fmac_f32_e32 v85, v71, v83
	v_cvt_pk_bf16_f32 v101, v84, v85
	v_lshlrev_b32_e32 v78, 16, v50
	v_and_b32_e32 v81, 0xffff0000, v50
	v_lshlrev_b32_e32 v79, 16, v54
	v_and_b32_e32 v82, 0xffff0000, v54
	v_lshlrev_b32_e32 v80, 16, v58
	v_and_b32_e32 v83, 0xffff0000, v58
	v_mul_f32_e32 v84, v69, v78
	v_mul_f32_e32 v85, v69, v81
	v_fmac_f32_e32 v84, v70, v79
	v_fmac_f32_e32 v85, v70, v82
	v_fmac_f32_e32 v84, v71, v80
	v_fmac_f32_e32 v85, v71, v83
	v_cvt_pk_bf16_f32 v102, v84, v85
	v_lshlrev_b32_e32 v78, 16, v51
	v_and_b32_e32 v81, 0xffff0000, v51
	v_lshlrev_b32_e32 v79, 16, v55
	v_and_b32_e32 v82, 0xffff0000, v55
	v_lshlrev_b32_e32 v80, 16, v59
	v_and_b32_e32 v83, 0xffff0000, v59
	v_mul_f32_e32 v84, v69, v78
	v_mul_f32_e32 v85, v69, v81
	v_fmac_f32_e32 v84, v70, v79
	v_fmac_f32_e32 v85, v70, v82
	v_fmac_f32_e32 v84, v71, v80
	v_fmac_f32_e32 v85, v71, v83
	v_cvt_pk_bf16_f32 v103, v84, v85
	s_add_u32 s26, s24, 0x2600000
	s_addc_u32 s27, s25, 0
	global_store_dwordx4 v64, v[100:103], s[26:27]
	s_add_u32 s26, s20, 0x2e00000
	s_addc_u32 s27, s21, 0
	global_load_dwordx4 v[48:51], v64, s[26:27]
	s_add_u32 s26, s20, 0x5e00000
	s_addc_u32 s27, s21, 0
	global_load_dwordx4 v[52:55], v64, s[26:27]
	s_add_u32 s26, s20, 0x8e00000
	s_addc_u32 s27, s21, 0
	global_load_dwordx4 v[56:59], v64, s[26:27]
	s_add_u32 s26, s22, 0x170000
	s_addc_u32 s27, s23, 0
	global_load_dword v60, v65, s[26:27]
	s_add_u32 s26, s22, 0x2f0000
	s_addc_u32 s27, s23, 0
	global_load_dword v61, v65, s[26:27]
	s_add_u32 s26, s22, 0x470000
	s_addc_u32 s27, s23, 0
	global_load_dword v62, v65, s[26:27]
	s_waitcnt vmcnt(21)
	v_max3_f32 v68, v12, v13, v14
	v_sub_f32_e32 v69, v12, v68
	v_sub_f32_e32 v70, v13, v68
	v_sub_f32_e32 v71, v14, v68
	v_mul_f32_e32 v69, 0x3fb8aa3b, v69
	v_mul_f32_e32 v70, 0x3fb8aa3b, v70
	v_mul_f32_e32 v71, 0x3fb8aa3b, v71
	v_exp_f32_e32 v69, v69
	v_exp_f32_e32 v70, v70
	v_exp_f32_e32 v71, v71
	s_nop 0
	v_add_f32_e32 v72, v69, v70
	v_add_f32_e32 v72, v71, v72
	v_div_scale_f32 v73, s[28:29], v72, v72, 1.0
	v_rcp_f32_e32 v74, v73
	v_div_scale_f32 v75, vcc, 1.0, v72, 1.0
	s_nop 0
	v_fma_f32 v76, -v73, v74, 1.0
	v_fmac_f32_e32 v74, v76, v74
	v_mul_f32_e32 v77, v75, v74
	v_fma_f32 v76, -v73, v77, v75
	v_fmac_f32_e32 v77, v76, v74
	v_fma_f32 v73, -v73, v77, v75
	v_div_fmas_f32 v73, v73, v74, v77
	v_div_fixup_f32 v72, v73, v72, 1.0
	v_mul_f32_e32 v69, v69, v72
	v_mul_f32_e32 v70, v70, v72
	v_mul_f32_e32 v71, v71, v72
	v_lshlrev_b32_e32 v78, 16, v0
	v_and_b32_e32 v81, 0xffff0000, v0
	v_lshlrev_b32_e32 v79, 16, v4
	v_and_b32_e32 v82, 0xffff0000, v4
	v_lshlrev_b32_e32 v80, 16, v8
	v_and_b32_e32 v83, 0xffff0000, v8
	v_mul_f32_e32 v84, v69, v78
	v_mul_f32_e32 v85, v69, v81
	v_fmac_f32_e32 v84, v70, v79
	v_fmac_f32_e32 v85, v70, v82
	v_fmac_f32_e32 v84, v71, v80
	v_fmac_f32_e32 v85, v71, v83
	v_cvt_pk_bf16_f32 v96, v84, v85
	v_lshlrev_b32_e32 v78, 16, v1
	v_and_b32_e32 v81, 0xffff0000, v1
	v_lshlrev_b32_e32 v79, 16, v5
	v_and_b32_e32 v82, 0xffff0000, v5
	v_lshlrev_b32_e32 v80, 16, v9
	v_and_b32_e32 v83, 0xffff0000, v9
	v_mul_f32_e32 v84, v69, v78
	v_mul_f32_e32 v85, v69, v81
	v_fmac_f32_e32 v84, v70, v79
	v_fmac_f32_e32 v85, v70, v82
	v_fmac_f32_e32 v84, v71, v80
	v_fmac_f32_e32 v85, v71, v83
	v_cvt_pk_bf16_f32 v97, v84, v85
	v_lshlrev_b32_e32 v78, 16, v2
	v_and_b32_e32 v81, 0xffff0000, v2
	v_lshlrev_b32_e32 v79, 16, v6
	v_and_b32_e32 v82, 0xffff0000, v6
	v_lshlrev_b32_e32 v80, 16, v10
	v_and_b32_e32 v83, 0xffff0000, v10
	v_mul_f32_e32 v84, v69, v78
	v_mul_f32_e32 v85, v69, v81
	v_fmac_f32_e32 v84, v70, v79
	v_fmac_f32_e32 v85, v70, v82
	v_fmac_f32_e32 v84, v71, v80
	v_fmac_f32_e32 v85, v71, v83
	v_cvt_pk_bf16_f32 v98, v84, v85
	v_lshlrev_b32_e32 v78, 16, v3
	v_and_b32_e32 v81, 0xffff0000, v3
	v_lshlrev_b32_e32 v79, 16, v7
	v_and_b32_e32 v82, 0xffff0000, v7
	v_lshlrev_b32_e32 v80, 16, v11
	v_and_b32_e32 v83, 0xffff0000, v11
	v_mul_f32_e32 v84, v69, v78
	v_mul_f32_e32 v85, v69, v81
	v_fmac_f32_e32 v84, v70, v79
	v_fmac_f32_e32 v85, v70, v82
	v_fmac_f32_e32 v84, v71, v80
	v_fmac_f32_e32 v85, v71, v83
	v_cvt_pk_bf16_f32 v99, v84, v85
	s_add_u32 s26, s24, 0x2800000
	s_addc_u32 s27, s25, 0
	global_store_dwordx4 v64, v[96:99], s[26:27]
	s_waitcnt vmcnt(15)
; __device__ __forceinline__ float bf_lo(unsigned w) { return __uint_as_float(w << 16); }
; __device__ __forceinline__ float bf_hi(unsigned w) { return __uint_as_float(w & 0xffff0000u); }
; __device__ __forceinline__ unsigned pk2(float lo, float hi) { return pg8::cvt_pk_bf16(lo, hi); }
; __device__ __forceinline__ void merge_rows(const Args& a, int gw, int NGW, int lane) {
;     ...
;         for (int r = 0; r < 4; ++r) { const int m = mb + r * NGW; if (m < MT) {
;             const float mxl = fmaxf(l[r][0], fmaxf(l[r][1], l[r][2]));
;             float a0 = __expf(l[r][0] - mxl), a1 = __expf(l[r][1] - mxl), a2 = __expf(l[r][2] - mxl); const float is = 1.0f / (a0 + a1 + a2); a0 *= is; a1 *= is; a2 *= is;
;             const v2u o0 = o[r][0], o1 = o[r][1], o2 = o[r][2];
;             v2u w;
;             w.x = pk2(a0 * pg8::bf_lo(o0.x) + a1 * pg8::bf_lo(o1.x) + a2 * pg8::bf_lo(o2.x), a0 * pg8::bf_hi(o0.x) + a1 * pg8::bf_hi(o1.x) + a2 * pg8::bf_hi(o2.x));
;             w.y = pk2(a0 * pg8::bf_lo(o0.y) + a1 * pg8::bf_lo(o1.y) + a2 * pg8::bf_lo(o2.y), a0 * pg8::bf_hi(o0.y) + a1 * pg8::bf_hi(o1.y) + a2 * pg8::bf_hi(o2.y));
;             *(v2u*)(YAT + (size_t)m * 256 + 4 * lane) = w; } }
	v_max3_f32 v68, v28, v29, v30
	v_sub_f32_e32 v69, v28, v68
	v_sub_f32_e32 v70, v29, v68
	v_sub_f32_e32 v71, v30, v68
	v_mul_f32_e32 v69, 0x3fb8aa3b, v69
	v_mul_f32_e32 v70, 0x3fb8aa3b, v70
	v_mul_f32_e32 v71, 0x3fb8aa3b, v71
	v_exp_f32_e32 v69, v69
	v_exp_f32_e32 v70, v70
	v_exp_f32_e32 v71, v71
	s_nop 0
	v_add_f32_e32 v72, v69, v70
	v_add_f32_e32 v72, v71, v72
	v_div_scale_f32 v73, s[28:29], v72, v72, 1.0
	v_rcp_f32_e32 v74, v73
	v_div_scale_f32 v75, vcc, 1.0, v72, 1.0
	s_nop 0
	v_fma_f32 v76, -v73, v74, 1.0
	v_fmac_f32_e32 v74, v76, v74
	v_mul_f32_e32 v77, v75, v74
	v_fma_f32 v76, -v73, v77, v75
	v_fmac_f32_e32 v77, v76, v74
	v_fma_f32 v73, -v73, v77, v75
	v_div_fmas_f32 v73, v73, v74, v77
	v_div_fixup_f32 v72, v73, v72, 1.0
	v_mul_f32_e32 v69, v69, v72
	v_mul_f32_e32 v70, v70, v72
	v_mul_f32_e32 v71, v71, v72
	v_lshlrev_b32_e32 v78, 16, v16
	v_and_b32_e32 v81, 0xffff0000, v16
	v_lshlrev_b32_e32 v79, 16, v20
	v_and_b32_e32 v82, 0xffff0000, v20
	v_lshlrev_b32_e32 v80, 16, v24
	v_and_b32_e32 v83, 0xffff0000, v24
	v_mul_f32_e32 v84, v69, v78
	v_mul_f32_e32 v85, v69, v81
	v_fmac_f32_e32 v84, v70, v79
	v_fmac_f32_e32 v85, v70, v82
	v_fmac_f32_e32 v84, v71, v80
	v_fmac_f32_e32 v85, v71, v83
	v_cvt_pk_bf16_f32 v100, v84, v85
	v_lshlrev_b32_e32 v78, 16, v17
	v_and_b32_e32 v81, 0xffff0000, v17
	v_lshlrev_b32_e32 v79, 16, v21
	v_and_b32_e32 v82, 0xffff0000, v21
	v_lshlrev_b32_e32 v80, 16, v25
	v_and_b32_e32 v83, 0xffff0000, v25
	v_mul_f32_e32 v84, v69, v78
	v_mul_f32_e32 v85, v69, v81
	v_fmac_f32_e32 v84, v70, v79
	v_fmac_f32_e32 v85, v70, v82
	v_fmac_f32_e32 v84, v71, v80
	v_fmac_f32_e32 v85, v71, v83
	v_cvt_pk_bf16_f32 v101, v84, v85
	v_lshlrev_b32_e32 v78, 16, v18
	v_and_b32_e32 v81, 0xffff0000, v18
	v_lshlrev_b32_e32 v79, 16, v22
	v_and_b32_e32 v82, 0xffff0000, v22
	v_lshlrev_b32_e32 v80, 16, v26
	v_and_b32_e32 v83, 0xffff0000, v26
	v_mul_f32_e32 v84, v69, v78
	v_mul_f32_e32 v85, v69, v81
	v_fmac_f32_e32 v84, v70, v79
	v_fmac_f32_e32 v85, v70, v82
	v_fmac_f32_e32 v84, v71, v80
	v_fmac_f32_e32 v85, v71, v83
	v_cvt_pk_bf16_f32 v102, v84, v85
	v_lshlrev_b32_e32 v78, 16, v19
	v_and_b32_e32 v81, 0xffff0000, v19
	v_lshlrev_b32_e32 v79, 16, v23
	v_and_b32_e32 v82, 0xffff0000, v23
	v_lshlrev_b32_e32 v80, 16, v27
	v_and_b32_e32 v83, 0xffff0000, v27
	v_mul_f32_e32 v84, v69, v78
	v_mul_f32_e32 v85, v69, v81
	v_fmac_f32_e32 v84, v70, v79
	v_fmac_f32_e32 v85, v70, v82
	v_fmac_f32_e32 v84, v71, v80
	v_fmac_f32_e32 v85, v71, v83
	v_cvt_pk_bf16_f32 v103, v84, v85
	s_add_u32 s26, s24, 0x2a00000
	s_addc_u32 s27, s25, 0
	global_store_dwordx4 v64, v[100:103], s[26:27]
	s_waitcnt vmcnt(9)
; __device__ __forceinline__ float bf_lo(unsigned w) { return __uint_as_float(w << 16); }
; __device__ __forceinline__ float bf_hi(unsigned w) { return __uint_as_float(w & 0xffff0000u); }
; __device__ __forceinline__ unsigned pk2(float lo, float hi) { return pg8::cvt_pk_bf16(lo, hi); }
; __device__ __forceinline__ void merge_rows(const Args& a, int gw, int NGW, int lane) {
;     ...
;         for (int r = 0; r < 4; ++r) { const int m = mb + r * NGW; if (m < MT) {
;             const float mxl = fmaxf(l[r][0], fmaxf(l[r][1], l[r][2]));
;             float a0 = __expf(l[r][0] - mxl), a1 = __expf(l[r][1] - mxl), a2 = __expf(l[r][2] - mxl); const float is = 1.0f / (a0 + a1 + a2); a0 *= is; a1 *= is; a2 *= is;
;             const v2u o0 = o[r][0], o1 = o[r][1], o2 = o[r][2];
;             v2u w;
;             w.x = pk2(a0 * pg8::bf_lo(o0.x) + a1 * pg8::bf_lo(o1.x) + a2 * pg8::bf_lo(o2.x), a0 * pg8::bf_hi(o0.x) + a1 * pg8::bf_hi(o1.x) + a2 * pg8::bf_hi(o2.x));
;             w.y = pk2(a0 * pg8::bf_lo(o0.y) + a1 * pg8::bf_lo(o1.y) + a2 * pg8::bf_lo(o2.y), a0 * pg8::bf_hi(o0.y) + a1 * pg8::bf_hi(o1.y) + a2 * pg8::bf_hi(o2.y));
;             *(v2u*)(YAT + (size_t)m * 256 + 4 * lane) = w; } }
	v_max3_f32 v68, v44, v45, v46
	v_sub_f32_e32 v69, v44, v68
	v_sub_f32_e32 v70, v45, v68
	v_sub_f32_e32 v71, v46, v68
	v_mul_f32_e32 v69, 0x3fb8aa3b, v69
	v_mul_f32_e32 v70, 0x3fb8aa3b, v70
	v_mul_f32_e32 v71, 0x3fb8aa3b, v71
	v_exp_f32_e32 v69, v69
	v_exp_f32_e32 v70, v70
	v_exp_f32_e32 v71, v71
	s_nop 0
	v_add_f32_e32 v72, v69, v70
	v_add_f32_e32 v72, v71, v72
	v_div_scale_f32 v73, s[28:29], v72, v72, 1.0
	v_rcp_f32_e32 v74, v73
	v_div_scale_f32 v75, vcc, 1.0, v72, 1.0
	s_nop 0
	v_fma_f32 v76, -v73, v74, 1.0
	v_fmac_f32_e32 v74, v76, v74
	v_mul_f32_e32 v77, v75, v74
	v_fma_f32 v76, -v73, v77, v75
	v_fmac_f32_e32 v77, v76, v74
	v_fma_f32 v73, -v73, v77, v75
	v_div_fmas_f32 v73, v73, v74, v77
	v_div_fixup_f32 v72, v73, v72, 1.0
	v_mul_f32_e32 v69, v69, v72
	v_mul_f32_e32 v70, v70, v72
	v_mul_f32_e32 v71, v71, v72
	v_lshlrev_b32_e32 v78, 16, v32
	v_and_b32_e32 v81, 0xffff0000, v32
	v_lshlrev_b32_e32 v79, 16, v36
	v_and_b32_e32 v82, 0xffff0000, v36
	v_lshlrev_b32_e32 v80, 16, v40
	v_and_b32_e32 v83, 0xffff0000, v40
	v_mul_f32_e32 v84, v69, v78
	v_mul_f32_e32 v85, v69, v81
	v_fmac_f32_e32 v84, v70, v79
	v_fmac_f32_e32 v85, v70, v82
	v_fmac_f32_e32 v84, v71, v80
	v_fmac_f32_e32 v85, v71, v83
	v_cvt_pk_bf16_f32 v96, v84, v85
	v_lshlrev_b32_e32 v78, 16, v33
	v_and_b32_e32 v81, 0xffff0000, v33
	v_lshlrev_b32_e32 v79, 16, v37
	v_and_b32_e32 v82, 0xffff0000, v37
	v_lshlrev_b32_e32 v80, 16, v41
	v_and_b32_e32 v83, 0xffff0000, v41
	v_mul_f32_e32 v84, v69, v78
	v_mul_f32_e32 v85, v69, v81
	v_fmac_f32_e32 v84, v70, v79
	v_fmac_f32_e32 v85, v70, v82
	v_fmac_f32_e32 v84, v71, v80
	v_fmac_f32_e32 v85, v71, v83
	v_cvt_pk_bf16_f32 v97, v84, v85
	v_lshlrev_b32_e32 v78, 16, v34
	v_and_b32_e32 v81, 0xffff0000, v34
	v_lshlrev_b32_e32 v79, 16, v38
	v_and_b32_e32 v82, 0xffff0000, v38
	v_lshlrev_b32_e32 v80, 16, v42
	v_and_b32_e32 v83, 0xffff0000, v42
	v_mul_f32_e32 v84, v69, v78
	v_mul_f32_e32 v85, v69, v81
	v_fmac_f32_e32 v84, v70, v79
	v_fmac_f32_e32 v85, v70, v82
	v_fmac_f32_e32 v84, v71, v80
	v_fmac_f32_e32 v85, v71, v83
	v_cvt_pk_bf16_f32 v98, v84, v85
	v_lshlrev_b32_e32 v78, 16, v35
	v_and_b32_e32 v81, 0xffff0000, v35
	v_lshlrev_b32_e32 v79, 16, v39
	v_and_b32_e32 v82, 0xffff0000, v39
	v_lshlrev_b32_e32 v80, 16, v43
	v_and_b32_e32 v83, 0xffff0000, v43
	v_mul_f32_e32 v84, v69, v78
	v_mul_f32_e32 v85, v69, v81
	v_fmac_f32_e32 v84, v70, v79
	v_fmac_f32_e32 v85, v70, v82
	v_fmac_f32_e32 v84, v71, v80
	v_fmac_f32_e32 v85, v71, v83
	v_cvt_pk_bf16_f32 v99, v84, v85
	s_add_u32 s26, s24, 0x2c00000
	s_addc_u32 s27, s25, 0
	global_store_dwordx4 v64, v[96:99], s[26:27]
	s_waitcnt vmcnt(3)
	v_max3_f32 v68, v60, v61, v62
	v_sub_f32_e32 v69, v60, v68
	v_sub_f32_e32 v70, v61, v68
	v_sub_f32_e32 v71, v62, v68
	v_mul_f32_e32 v69, 0x3fb8aa3b, v69
	v_mul_f32_e32 v70, 0x3fb8aa3b, v70
	v_mul_f32_e32 v71, 0x3fb8aa3b, v71
	v_exp_f32_e32 v69, v69
	v_exp_f32_e32 v70, v70
	v_exp_f32_e32 v71, v71
	s_nop 0
	v_add_f32_e32 v72, v69, v70
	v_add_f32_e32 v72, v71, v72
	v_div_scale_f32 v73, s[28:29], v72, v72, 1.0
	v_rcp_f32_e32 v74, v73
	v_div_scale_f32 v75, vcc, 1.0, v72, 1.0
	s_nop 0
	v_fma_f32 v76, -v73, v74, 1.0
	v_fmac_f32_e32 v74, v76, v74
	v_mul_f32_e32 v77, v75, v74
	v_fma_f32 v76, -v73, v77, v75
	v_fmac_f32_e32 v77, v76, v74
	v_fma_f32 v73, -v73, v77, v75
	v_div_fmas_f32 v73, v73, v74, v77
	v_div_fixup_f32 v72, v73, v72, 1.0
	v_mul_f32_e32 v69, v69, v72
	v_mul_f32_e32 v70, v70, v72
	v_mul_f32_e32 v71, v71, v72
	v_lshlrev_b32_e32 v78, 16, v48
	v_and_b32_e32 v81, 0xffff0000, v48
	v_lshlrev_b32_e32 v79, 16, v52
	v_and_b32_e32 v82, 0xffff0000, v52
	v_lshlrev_b32_e32 v80, 16, v56
	v_and_b32_e32 v83, 0xffff0000, v56
	v_mul_f32_e32 v84, v69, v78
	v_mul_f32_e32 v85, v69, v81
	v_fmac_f32_e32 v84, v70, v79
	v_fmac_f32_e32 v85, v70, v82
	v_fmac_f32_e32 v84, v71, v80
	v_fmac_f32_e32 v85, v71, v83
	v_cvt_pk_bf16_f32 v100, v84, v85
	v_lshlrev_b32_e32 v78, 16, v49
	v_and_b32_e32 v81, 0xffff0000, v49
	v_lshlrev_b32_e32 v79, 16, v53
	v_and_b32_e32 v82, 0xffff0000, v53
	v_lshlrev_b32_e32 v80, 16, v57
	v_and_b32_e32 v83, 0xffff0000, v57
	v_mul_f32_e32 v84, v69, v78
	v_mul_f32_e32 v85, v69, v81
	v_fmac_f32_e32 v84, v70, v79
	v_fmac_f32_e32 v85, v70, v82
	v_fmac_f32_e32 v84, v71, v80
	v_fmac_f32_e32 v85, v71, v83
	v_cvt_pk_bf16_f32 v101, v84, v85
	v_lshlrev_b32_e32 v78, 16, v50
	v_and_b32_e32 v81, 0xffff0000, v50
	v_lshlrev_b32_e32 v79, 16, v54
	v_and_b32_e32 v82, 0xffff0000, v54
	v_lshlrev_b32_e32 v80, 16, v58
	v_and_b32_e32 v83, 0xffff0000, v58
	v_mul_f32_e32 v84, v69, v78
	v_mul_f32_e32 v85, v69, v81
	v_fmac_f32_e32 v84, v70, v79
	v_fmac_f32_e32 v85, v70, v82
	v_fmac_f32_e32 v84, v71, v80
	v_fmac_f32_e32 v85, v71, v83
	v_cvt_pk_bf16_f32 v102, v84, v85
	v_lshlrev_b32_e32 v78, 16, v51
	v_and_b32_e32 v81, 0xffff0000, v51
	v_lshlrev_b32_e32 v79, 16, v55
	v_and_b32_e32 v82, 0xffff0000, v55
	v_lshlrev_b32_e32 v80, 16, v59
	v_and_b32_e32 v83, 0xffff0000, v59
	v_mul_f32_e32 v84, v69, v78
	v_mul_f32_e32 v85, v69, v81
	v_fmac_f32_e32 v84, v70, v79
	v_fmac_f32_e32 v85, v70, v82
	v_fmac_f32_e32 v84, v71, v80
	v_fmac_f32_e32 v85, v71, v83
	v_cvt_pk_bf16_f32 v103, v84, v85
	s_add_u32 s26, s24, 0x2e00000
	s_addc_u32 s27, s25, 0
	global_store_dwordx4 v64, v[100:103], s[26:27]
